# DPP wave sums in lnmix/lnffn; P0 MoE loop counted vmcnt; r2 token loop rewritten with 40 loads in flight
# speedup vs baseline: 1.0329x; 1.0111x over previous
.LBB0_69:
	s_or_b64 exec, exec, s[0:1]
	s_and_saveexec_b64 s[6:7], vcc
	s_cbranch_execz .LBB0_86
	v_lshlrev_b32_e32 v0, 4, v85
	v_lshrrev_b32_e32 v75, 4, v83
	v_and_b32_e32 v0, 0xf0, v0
	v_add_u32_e32 v0, v84, v0
	v_accvgpr_write_b32 a1, v75
	v_mul_u32_u24_e32 v75, 0x104, v75
	v_add_u32_e32 v75, v0, v75
	v_add_u32_e32 v0, 0x410, v75
	v_accvgpr_write_b32 a3, v0
	v_add_u32_e32 v0, 0x418, v75
	v_accvgpr_write_b32 a5, v0
	v_add_u32_e32 v0, 0x820, v75
	v_accvgpr_write_b32 a7, v0
	v_add_u32_e32 v0, 0x828, v75
	v_accvgpr_write_b32 a9, v0
	v_add_u32_e32 v0, 0xc30, v75
	v_accvgpr_write_b32 a10, v0
	v_add_u32_e32 v0, 0xc38, v75
	v_accvgpr_write_b32 a11, v0
	v_add_u32_e32 v0, 0x1040, v75
	v_accvgpr_write_b32 a12, v0
	v_add_u32_e32 v0, 0x1048, v75
	v_accvgpr_write_b32 a13, v0
	v_add_u32_e32 v0, 0x1450, v75
	v_accvgpr_write_b32 a18, v0
	v_add_u32_e32 v0, 0x1458, v75
	v_accvgpr_write_b32 a19, v0
	v_add_u32_e32 v0, 0x1860, v75
	v_accvgpr_write_b32 a20, v0
	v_add_u32_e32 v0, 0x1868, v75
	v_accvgpr_write_b32 a21, v0
	v_add_u32_e32 v0, 0x1c70, v75
	v_accvgpr_write_b32 a22, v0
	v_add_u32_e32 v0, 0x1c78, v75
	v_accvgpr_write_b32 a23, v0
	v_add_u32_e32 v0, 0x2080, v75
	v_accvgpr_write_b32 a24, v0
	v_add_u32_e32 v0, 0x2088, v75
	v_accvgpr_write_b32 a25, v0
	v_add_u32_e32 v0, 0x2490, v75
	v_accvgpr_write_b32 a30, v0
	v_add_u32_e32 v0, 0x2498, v75
	v_accvgpr_write_b32 a31, v0
	v_add_u32_e32 v0, 0x28a0, v75
	v_accvgpr_write_b32 a32, v0
	v_add_u32_e32 v0, 0x28a8, v75
	v_accvgpr_write_b32 a33, v0
	v_add_u32_e32 v0, 0x2cb0, v75
	v_accvgpr_write_b32 a34, v0
	v_add_u32_e32 v0, 0x2cb8, v75
	v_accvgpr_write_b32 a35, v0
	v_add_u32_e32 v0, 0x30c0, v75
	v_accvgpr_write_b32 a40, v0
	v_add_u32_e32 v0, 0x30c8, v75
	v_lshlrev_b32_e32 v1, 2, v83
	v_accvgpr_write_b32 a41, v0
	v_add_u32_e32 v0, 0x34d0, v75
	v_and_b32_e32 v74, 60, v1
	v_and_b32_e32 v71, 3, v85
	v_accvgpr_write_b32 a42, v0
	v_add_u32_e32 v0, 0x34d8, v75
	v_accvgpr_write_b32 a2, v74
	v_lshrrev_b32_e32 v74, 2, v83
	v_lshlrev_b32_e32 v86, 4, v71
	v_mul_u32_u24_e32 v71, 0x1040, v71
	v_and_b32_e32 v76, 60, v83
	v_accvgpr_write_b32 a43, v0
	v_add_u32_e32 v0, 0x38e0, v75
	v_readlane_b32 s0, v127, 17
	v_add3_u32 v76, v84, v71, v76
	v_or_b32_e32 v84, 16, v74
	v_readlane_b32 s8, v126, 2
	v_accvgpr_write_b32 a44, v0
	v_add_u32_e32 v0, 0x38e8, v75
	s_lshl_b32 s3, s0, 4
	v_accvgpr_write_b32 a4, v84
	v_or_b32_e32 v84, 32, v74
	v_readlane_b32 s14, v126, 8
	v_lshlrev_b32_e32 v71, 2, v82
	v_accvgpr_write_b32 a45, v0
	v_add_u32_e32 v0, 0x3cf0, v75
	v_mov_b32_e32 v1, 0
	v_accvgpr_write_b32 a6, v84
	v_or_b32_e32 v84, 48, v74
	v_readlane_b32 s9, v126, 3
	v_readlane_b32 s10, v126, 4
	v_readlane_b32 s11, v126, 5
	v_readlane_b32 s15, v126, 9
	s_add_u32 s8, s14, 0x10000000
	v_lshl_add_u32 v89, s2, 5, v71
	v_lshlrev_b32_e32 v71, 6, v82
	v_accvgpr_write_b32 a50, v0
	v_add_u32_e32 v0, 0x3cf8, v75
	v_mov_b32_e32 v87, v1
	v_accvgpr_write_b32 a8, v84
	s_addc_u32 s9, s15, 0
	s_mul_i32 s14, s0, 24
	s_mul_i32 s15, s0, 0x60
	s_lshl_b32 s16, s0, 6
	s_mul_i32 s17, s0, 0x600
	v_lshl_add_u32 v71, s2, 9, v71
	s_lshl_b32 s18, s0, 10
	s_mov_b64 s[10:11], 0
	v_accvgpr_write_b32 a51, v0
	s_mov_b32 s19, 0xc000
	s_mov_b32 s20, 0xbfff
	s_movk_i32 s21, 0x7fff
	s_movk_i32 s22, 0x3fff
	v_mov_b32_e32 v90, v88
	v_mov_b64_e32 v[82:83], v[80:81]
	v_readlane_b32 s12, v126, 6
	v_readlane_b32 s13, v126, 7
	s_waitcnt vmcnt(16)
	s_mov_b32 s39, 0
	s_mov_b32 s38, 0
	s_branch .LBB0_74

.LBB0_73:
	s_or_b64 exec, exec, s[4:5]
	s_add_i32 s39, s39, 1
	v_add_u32_e32 v89, s16, v89
	v_add_u32_e32 v71, s18, v71
	v_mov_b32_e32 v88, v90
	v_mov_b64_e32 v[80:81], v[82:83]
	v_mov_b32_e32 v92, v91
	s_andn2_b64 exec, exec, s[10:11]
	s_cbranch_execz .LBB0_86
.LBB0_74:
	s_waitcnt vmcnt(39)
	v_pk_mul_f32 v[84:85], v[2:3], v[70:71] op_sel_hi:[1,0]
	ds_write2_b32 v75, v84, v85 offset1:1
	v_pk_mul_f32 v[84:85], v[4:5], v[70:71] op_sel_hi:[1,0]
	ds_write2_b32 v75, v84, v85 offset0:2 offset1:3
	s_waitcnt vmcnt(38)
	v_pk_mul_f32 v[84:85], v[6:7], v[70:71] op_sel_hi:[1,0]
	v_accvgpr_read_b32 v0, a3
	ds_write2_b32 v0, v84, v85 offset1:1
	v_pk_mul_f32 v[84:85], v[8:9], v[70:71] op_sel_hi:[1,0]
	v_accvgpr_read_b32 v0, a5
	ds_write2_b32 v0, v84, v85 offset1:1
	s_waitcnt vmcnt(37)
	v_pk_mul_f32 v[84:85], v[10:11], v[70:71] op_sel_hi:[1,0]
	v_accvgpr_read_b32 v0, a7
	ds_write2_b32 v0, v84, v85 offset1:1
	v_pk_mul_f32 v[84:85], v[12:13], v[70:71] op_sel_hi:[1,0]
	v_accvgpr_read_b32 v0, a9
	ds_write2_b32 v0, v84, v85 offset1:1
	s_waitcnt vmcnt(36)
	v_pk_mul_f32 v[84:85], v[14:15], v[70:71] op_sel_hi:[1,0]
	v_accvgpr_read_b32 v0, a10
	ds_write2_b32 v0, v84, v85 offset1:1
	v_pk_mul_f32 v[84:85], v[16:17], v[70:71] op_sel_hi:[1,0]
	v_accvgpr_read_b32 v0, a11
	ds_write2_b32 v0, v84, v85 offset1:1
	s_waitcnt vmcnt(35)
	v_pk_mul_f32 v[84:85], v[18:19], v[70:71] op_sel_hi:[1,0]
	v_accvgpr_read_b32 v0, a12
	ds_write2_b32 v0, v84, v85 offset1:1
	v_pk_mul_f32 v[84:85], v[20:21], v[70:71] op_sel_hi:[1,0]
	v_accvgpr_read_b32 v0, a13
	ds_write2_b32 v0, v84, v85 offset1:1
	s_waitcnt vmcnt(34)
	v_pk_mul_f32 v[84:85], v[22:23], v[70:71] op_sel_hi:[1,0]
	v_accvgpr_read_b32 v0, a18
	ds_write2_b32 v0, v84, v85 offset1:1
	v_pk_mul_f32 v[84:85], v[24:25], v[70:71] op_sel_hi:[1,0]
	v_accvgpr_read_b32 v0, a19
	ds_write2_b32 v0, v84, v85 offset1:1
	s_waitcnt vmcnt(33)
	v_pk_mul_f32 v[84:85], v[26:27], v[70:71] op_sel_hi:[1,0]
	v_accvgpr_read_b32 v0, a20
	ds_write2_b32 v0, v84, v85 offset1:1
	v_pk_mul_f32 v[84:85], v[28:29], v[70:71] op_sel_hi:[1,0]
	v_accvgpr_read_b32 v0, a21
	ds_write2_b32 v0, v84, v85 offset1:1
	s_waitcnt vmcnt(32)
	v_pk_mul_f32 v[84:85], v[30:31], v[70:71] op_sel_hi:[1,0]
	v_accvgpr_read_b32 v0, a22
	ds_write2_b32 v0, v84, v85 offset1:1
	v_pk_mul_f32 v[84:85], v[32:33], v[70:71] op_sel_hi:[1,0]
	v_accvgpr_read_b32 v0, a23
	ds_write2_b32 v0, v84, v85 offset1:1
	s_waitcnt vmcnt(31)
	v_pk_mul_f32 v[84:85], v[34:35], v[70:71] op_sel_hi:[1,0]
	v_accvgpr_read_b32 v0, a24
	ds_write2_b32 v0, v84, v85 offset1:1
	v_pk_mul_f32 v[84:85], v[36:37], v[70:71] op_sel_hi:[1,0]
	v_accvgpr_read_b32 v0, a25
	ds_write2_b32 v0, v84, v85 offset1:1
	s_waitcnt vmcnt(30)
	v_pk_mul_f32 v[84:85], v[38:39], v[70:71] op_sel_hi:[1,0]
	v_accvgpr_read_b32 v0, a30
	ds_write2_b32 v0, v84, v85 offset1:1
	v_pk_mul_f32 v[84:85], v[40:41], v[70:71] op_sel_hi:[1,0]
	v_accvgpr_read_b32 v0, a31
	ds_write2_b32 v0, v84, v85 offset1:1
	s_waitcnt vmcnt(29)
	v_pk_mul_f32 v[84:85], v[42:43], v[70:71] op_sel_hi:[1,0]
	v_accvgpr_read_b32 v0, a32
	ds_write2_b32 v0, v84, v85 offset1:1
	v_pk_mul_f32 v[84:85], v[44:45], v[70:71] op_sel_hi:[1,0]
	v_accvgpr_read_b32 v0, a33
	ds_write2_b32 v0, v84, v85 offset1:1
	s_waitcnt vmcnt(28)
	v_pk_mul_f32 v[84:85], v[46:47], v[70:71] op_sel_hi:[1,0]
	v_accvgpr_read_b32 v0, a34
	ds_write2_b32 v0, v84, v85 offset1:1
	v_pk_mul_f32 v[84:85], v[48:49], v[70:71] op_sel_hi:[1,0]
	v_accvgpr_read_b32 v0, a35
	ds_write2_b32 v0, v84, v85 offset1:1
	s_waitcnt vmcnt(27)
	v_pk_mul_f32 v[84:85], v[50:51], v[70:71] op_sel_hi:[1,0]
	v_accvgpr_read_b32 v0, a40
	ds_write2_b32 v0, v84, v85 offset1:1
	v_pk_mul_f32 v[84:85], v[52:53], v[70:71] op_sel_hi:[1,0]
	v_accvgpr_read_b32 v0, a41
	ds_write2_b32 v0, v84, v85 offset1:1
	s_waitcnt vmcnt(26)
	v_pk_mul_f32 v[84:85], v[54:55], v[70:71] op_sel_hi:[1,0]
	v_accvgpr_read_b32 v0, a42
	ds_write2_b32 v0, v84, v85 offset1:1
	v_pk_mul_f32 v[84:85], v[56:57], v[70:71] op_sel_hi:[1,0]
	v_accvgpr_read_b32 v0, a43
	ds_write2_b32 v0, v84, v85 offset1:1
	s_waitcnt vmcnt(25)
	v_pk_mul_f32 v[84:85], v[58:59], v[70:71] op_sel_hi:[1,0]
	v_accvgpr_read_b32 v0, a44
	ds_write2_b32 v0, v84, v85 offset1:1
	v_pk_mul_f32 v[84:85], v[60:61], v[70:71] op_sel_hi:[1,0]
	v_accvgpr_read_b32 v0, a45
	ds_write2_b32 v0, v84, v85 offset1:1
	s_waitcnt vmcnt(24)
	v_pk_mul_f32 v[84:85], v[62:63], v[70:71] op_sel_hi:[1,0]
	v_accvgpr_read_b32 v0, a50
	v_add_u32_e32 v91, s3, v92
	ds_write2_b32 v0, v84, v85 offset1:1
	v_pk_mul_f32 v[84:85], v[64:65], v[70:71] op_sel_hi:[1,0]
	v_accvgpr_read_b32 v0, a51
	v_cmp_gt_i32_e64 s[4:5], s19, v91
	v_cmp_lt_i32_e32 vcc, s20, v91
	ds_write2_b32 v0, v84, v85 offset1:1
	s_and_saveexec_b64 s[0:1], s[4:5]
	s_cselect_b32 s38, 0, 1
	s_cbranch_execz .LBB0_80
	v_cmp_lt_i32_e64 s[4:5], s21, v91
	s_and_saveexec_b64 s[12:13], s[4:5]
	s_xor_b64 s[4:5], exec, s[12:13]
	s_cbranch_execz .LBB0_77
	v_add_u32_e32 v2, s18, v71
	v_add_u32_e32 v0, 0xffff8000, v91
	v_and_b32_e32 v6, 0x3c0, v2
	v_add_u32_e32 v2, s16, v89
	v_lshrrev_b32_e32 v0, 9, v0
	v_and_b32_e32 v82, 0x7c0, v2
	v_readlane_b32 s24, v126, 2
	v_accvgpr_read_b32 v4, a1
	v_lshlrev_b64 v[2:3], 23, v[0:1]
	v_readlane_b32 s26, v126, 4
	v_readlane_b32 s27, v126, 5
	v_or_b32_e32 v4, v82, v4
	v_lshlrev_b32_e32 v4, 12, v4
	v_lshl_add_u64 v[2:3], s[26:27], 0, v[2:3]
	v_mov_b32_e32 v5, v1
	v_lshl_add_u64 v[2:3], v[2:3], 0, v[4:5]
	v_lshlrev_b32_e32 v4, 2, v6
	v_lshl_add_u64 v[2:3], v[2:3], 0, v[4:5]
	v_lshlrev_b64 v[4:5], 21, v[0:1]
	v_lshl_add_u64 v[4:5], s[8:9], 0, v[4:5]
	v_lshlrev_b32_e32 v0, 11, v6
	v_readlane_b32 s25, v126, 3
	v_readlane_b32 s28, v126, 6
	v_readlane_b32 s29, v126, 7
	v_readlane_b32 s30, v126, 8
	v_readlane_b32 s31, v126, 9
	v_lshl_add_u64 v[84:85], v[4:5], 0, v[0:1]

.LBB0_80:
	s_or_b64 exec, exec, s[0:1]
	s_waitcnt lgkmcnt(0)
	ds_read2_b32 v[84:85], v76 offset1:65
	ds_read2_b32 v[94:95], v76 offset0:130 offset1:195
	v_mov_b32_e32 v96, v1
	v_mov_b32_e32 v0, v92
	v_add_u32_e32 v92, 0x400, v76
	s_waitcnt lgkmcnt(1)
	v_cvt_pk_fp8_f32 v96, v84, v85
	v_mov_b32_e32 v97, v1
	s_waitcnt lgkmcnt(0)
	v_cvt_pk_fp8_f32 v96, v94, v95 op_sel:[0,0,1]
	ds_read2_b32 v[84:85], v92 offset0:4 offset1:69
	ds_read2_b32 v[94:95], v92 offset0:134 offset1:199
	v_add_u32_e32 v93, 0x800, v76
	s_waitcnt lgkmcnt(1)
	v_cvt_pk_fp8_f32 v97, v84, v85
	s_waitcnt lgkmcnt(0)
	v_cvt_pk_fp8_f32 v97, v94, v95 op_sel:[0,0,1]
	ds_read2_b32 v[84:85], v93 offset0:8 offset1:73
	ds_read2_b32 v[100:101], v93 offset0:138 offset1:203
	v_mov_b32_e32 v98, v1
	v_add_u32_e32 v94, 0xc00, v76
	s_waitcnt lgkmcnt(1)
	v_cvt_pk_fp8_f32 v98, v84, v85
	s_waitcnt lgkmcnt(0)
	v_cvt_pk_fp8_f32 v98, v100, v101 op_sel:[0,0,1]
	ds_read2_b32 v[84:85], v94 offset0:12 offset1:77
	ds_read2_b32 v[100:101], v94 offset0:142 offset1:207
	v_mov_b32_e32 v99, v1
	s_waitcnt lgkmcnt(1)
	v_cvt_pk_fp8_f32 v99, v84, v85
	s_waitcnt lgkmcnt(0)
	v_cvt_pk_fp8_f32 v99, v100, v101 op_sel:[0,0,1]
	ds_read2_b32 v[84:85], v76 offset0:16 offset1:81
	ds_read2_b32 v[100:101], v76 offset0:146 offset1:211
	s_and_b64 s[0:1], exec, vcc
	v_lshl_add_u64 v[80:81], v[80:81], 0, v[86:87]
	s_or_b64 s[10:11], s[0:1], s[10:11]
	v_mad_i64_i32 v[102:103], s[0:1], v88, v74, v[80:81]
	global_store_dwordx4 v[102:103], v[96:99], off nt
	v_accvgpr_read_b32 v102, a4
	v_mad_i64_i32 v[102:103], s[0:1], v88, v102, v[80:81]
	v_mov_b32_e32 v96, v1
	s_waitcnt lgkmcnt(1)
	v_cvt_pk_fp8_f32 v96, v84, v85
	v_mov_b32_e32 v97, v1
	s_waitcnt lgkmcnt(0)
	v_cvt_pk_fp8_f32 v96, v100, v101 op_sel:[0,0,1]
	ds_read2_b32 v[84:85], v92 offset0:20 offset1:85
	ds_read2_b32 v[98:99], v92 offset0:150 offset1:215
	s_waitcnt lgkmcnt(1)
	v_cvt_pk_fp8_f32 v97, v84, v85
	s_waitcnt lgkmcnt(0)
	v_cvt_pk_fp8_f32 v97, v98, v99 op_sel:[0,0,1]
	ds_read2_b32 v[84:85], v93 offset0:24 offset1:89
	ds_read2_b32 v[100:101], v93 offset0:154 offset1:219
	v_mov_b32_e32 v98, v1
	s_waitcnt lgkmcnt(1)
	v_cvt_pk_fp8_f32 v98, v84, v85
	s_waitcnt lgkmcnt(0)
	v_cvt_pk_fp8_f32 v98, v100, v101 op_sel:[0,0,1]
	ds_read2_b32 v[84:85], v94 offset0:28 offset1:93
	ds_read2_b32 v[100:101], v94 offset0:158 offset1:223
	v_mov_b32_e32 v99, v1
	s_waitcnt lgkmcnt(1)
	v_cvt_pk_fp8_f32 v99, v84, v85
	s_waitcnt lgkmcnt(0)
	v_cvt_pk_fp8_f32 v99, v100, v101 op_sel:[0,0,1]
	ds_read2_b32 v[84:85], v76 offset0:32 offset1:97
	ds_read2_b32 v[100:101], v76 offset0:162 offset1:227
	global_store_dwordx4 v[102:103], v[96:99], off nt
	v_accvgpr_read_b32 v104, a6
	v_mad_i64_i32 v[104:105], s[0:1], v88, v104, v[80:81]
	v_mov_b32_e32 v96, v1
	s_waitcnt lgkmcnt(1)
	v_cvt_pk_fp8_f32 v96, v84, v85
	v_mov_b32_e32 v97, v1
	s_waitcnt lgkmcnt(0)
	v_cvt_pk_fp8_f32 v96, v100, v101 op_sel:[0,0,1]
	ds_read2_b32 v[84:85], v92 offset0:36 offset1:101
	ds_read2_b32 v[98:99], v92 offset0:166 offset1:231
	s_waitcnt lgkmcnt(1)
	v_cvt_pk_fp8_f32 v97, v84, v85
	s_waitcnt lgkmcnt(0)
	v_cvt_pk_fp8_f32 v97, v98, v99 op_sel:[0,0,1]
	ds_read2_b32 v[84:85], v93 offset0:40 offset1:105
	ds_read2_b32 v[100:101], v93 offset0:170 offset1:235
	v_mov_b32_e32 v98, v1
	s_waitcnt lgkmcnt(1)
	v_cvt_pk_fp8_f32 v98, v84, v85
	s_waitcnt lgkmcnt(0)
	v_cvt_pk_fp8_f32 v98, v100, v101 op_sel:[0,0,1]
	ds_read2_b32 v[84:85], v94 offset0:44 offset1:109
	ds_read2_b32 v[102:103], v94 offset0:174 offset1:239
	v_mov_b32_e32 v99, v1
	s_waitcnt lgkmcnt(1)
	v_cvt_pk_fp8_f32 v99, v84, v85
	s_waitcnt lgkmcnt(0)
	v_cvt_pk_fp8_f32 v99, v102, v103 op_sel:[0,0,1]
	ds_read2_b32 v[84:85], v76 offset0:48 offset1:113
	ds_read2_b32 v[102:103], v76 offset0:178 offset1:243
	v_mov_b32_e32 v100, v1
	global_store_dwordx4 v[104:105], v[96:99], off nt
	s_waitcnt lgkmcnt(1)
	v_cvt_pk_fp8_f32 v100, v84, v85
	s_waitcnt lgkmcnt(0)
	v_cvt_pk_fp8_f32 v100, v102, v103 op_sel:[0,0,1]
	ds_read2_b32 v[84:85], v92 offset0:52 offset1:117
	ds_read2_b32 v[96:97], v92 offset0:182 offset1:247
	v_mov_b32_e32 v101, v1
	s_waitcnt lgkmcnt(1)
	v_cvt_pk_fp8_f32 v101, v84, v85
	s_waitcnt lgkmcnt(0)
	v_cvt_pk_fp8_f32 v101, v96, v97 op_sel:[0,0,1]
	ds_read2_b32 v[84:85], v93 offset0:56 offset1:121
	ds_read2_b32 v[96:97], v93 offset0:186 offset1:251
	v_mov_b32_e32 v102, v1
	s_waitcnt lgkmcnt(1)
	v_cvt_pk_fp8_f32 v102, v84, v85
	s_waitcnt lgkmcnt(0)
	v_cvt_pk_fp8_f32 v102, v96, v97 op_sel:[0,0,1]
	ds_read2_b32 v[84:85], v94 offset0:60 offset1:125
	ds_read2_b32 v[96:97], v94 offset0:190 offset1:255
	v_mov_b32_e32 v103, v1
	s_waitcnt lgkmcnt(1)
	v_cvt_pk_fp8_f32 v103, v84, v85
	v_accvgpr_read_b32 v84, a8
	v_mad_i64_i32 v[80:81], s[0:1], v88, v84, v[80:81]
	s_waitcnt lgkmcnt(0)
	v_cvt_pk_fp8_f32 v103, v96, v97 op_sel:[0,0,1]
	global_store_dwordx4 v[80:81], v[100:103], off nt
	s_waitcnt lgkmcnt(0)
	v_mov_b32_e32 v84, v0
	v_add_u32_e32 v0, s80, v84
	v_cmp_gt_i32_e32 vcc, s19, v0
	s_and_saveexec_b64 s[4:5], vcc
	s_cbranch_execz .LBB0_73
	s_cmp_eq_u32 s39, 0
	s_cselect_b32 s37, 1, s38
	s_cmp_eq_u32 s37, 0
	s_cbranch_scc1 .Lp0_w24
	s_waitcnt vmcnt(8)
	s_branch .Lp0_wdone
.Lp0_w24:
	s_waitcnt vmcnt(24)
.Lp0_wdone:
	v_accvgpr_read_b32 v99, a17
	v_accvgpr_read_b32 v97, a15
	v_accvgpr_read_b32 v96, a14
	v_accvgpr_read_b32 v98, a16
	v_pk_mul_f32 v[80:81], v[96:97], v[72:73] op_sel_hi:[1,0]
	ds_write2_b32 v75, v80, v81 offset1:1
	v_pk_mul_f32 v[80:81], v[98:99], v[72:73] op_sel_hi:[1,0]
	v_accvgpr_read_b32 v99, a29
	v_accvgpr_read_b32 v97, a27
	v_accvgpr_read_b32 v96, a26
	ds_write2_b32 v75, v80, v81 offset0:2 offset1:3
	v_accvgpr_read_b32 v98, a28
	v_pk_mul_f32 v[80:81], v[96:97], v[72:73] op_sel_hi:[1,0]
	v_accvgpr_read_b32 v0, a3
	ds_write2_b32 v0, v80, v81 offset1:1
	v_pk_mul_f32 v[80:81], v[98:99], v[72:73] op_sel_hi:[1,0]
	v_accvgpr_read_b32 v99, a39
	v_accvgpr_read_b32 v0, a5
	v_accvgpr_read_b32 v97, a37
	v_accvgpr_read_b32 v96, a36
	ds_write2_b32 v0, v80, v81 offset1:1
	v_accvgpr_read_b32 v98, a38
	v_pk_mul_f32 v[80:81], v[96:97], v[72:73] op_sel_hi:[1,0]
	v_accvgpr_read_b32 v0, a7
	ds_write2_b32 v0, v80, v81 offset1:1
	v_pk_mul_f32 v[80:81], v[98:99], v[72:73] op_sel_hi:[1,0]
	v_accvgpr_read_b32 v99, a49
	v_accvgpr_read_b32 v0, a9
	v_accvgpr_read_b32 v97, a47
	v_accvgpr_read_b32 v96, a46
	ds_write2_b32 v0, v80, v81 offset1:1
	v_accvgpr_read_b32 v98, a48
	v_pk_mul_f32 v[80:81], v[96:97], v[72:73] op_sel_hi:[1,0]
	v_accvgpr_read_b32 v0, a10
	ds_write2_b32 v0, v80, v81 offset1:1
	v_pk_mul_f32 v[80:81], v[98:99], v[72:73] op_sel_hi:[1,0]
	v_accvgpr_read_b32 v99, a55
	v_accvgpr_read_b32 v0, a11
	v_accvgpr_read_b32 v97, a53
	v_accvgpr_read_b32 v96, a52
	ds_write2_b32 v0, v80, v81 offset1:1
	v_accvgpr_read_b32 v98, a54
	v_pk_mul_f32 v[80:81], v[96:97], v[72:73] op_sel_hi:[1,0]
	v_accvgpr_read_b32 v0, a12
	ds_write2_b32 v0, v80, v81 offset1:1
	v_pk_mul_f32 v[80:81], v[98:99], v[72:73] op_sel_hi:[1,0]
	v_accvgpr_read_b32 v99, a59
	v_accvgpr_read_b32 v0, a13
	v_accvgpr_read_b32 v97, a57
	v_accvgpr_read_b32 v96, a56
	ds_write2_b32 v0, v80, v81 offset1:1
	v_accvgpr_read_b32 v98, a58
	v_pk_mul_f32 v[80:81], v[96:97], v[72:73] op_sel_hi:[1,0]
	v_accvgpr_read_b32 v0, a18
	ds_write2_b32 v0, v80, v81 offset1:1
	v_pk_mul_f32 v[80:81], v[98:99], v[72:73] op_sel_hi:[1,0]
	v_accvgpr_read_b32 v99, a63
	v_accvgpr_read_b32 v0, a19
	v_accvgpr_read_b32 v97, a61
	v_accvgpr_read_b32 v96, a60
	ds_write2_b32 v0, v80, v81 offset1:1
	v_accvgpr_read_b32 v98, a62
	v_pk_mul_f32 v[80:81], v[96:97], v[72:73] op_sel_hi:[1,0]
	v_accvgpr_read_b32 v0, a20
	ds_write2_b32 v0, v80, v81 offset1:1
	v_pk_mul_f32 v[80:81], v[98:99], v[72:73] op_sel_hi:[1,0]
	v_accvgpr_read_b32 v99, a67
	v_accvgpr_read_b32 v0, a21
	v_accvgpr_read_b32 v97, a65
	v_accvgpr_read_b32 v96, a64
	ds_write2_b32 v0, v80, v81 offset1:1
	v_accvgpr_read_b32 v98, a66
	v_pk_mul_f32 v[80:81], v[96:97], v[72:73] op_sel_hi:[1,0]
	v_accvgpr_read_b32 v0, a22
	ds_write2_b32 v0, v80, v81 offset1:1
	v_pk_mul_f32 v[80:81], v[98:99], v[72:73] op_sel_hi:[1,0]
	v_accvgpr_read_b32 v99, a71
	v_accvgpr_read_b32 v0, a23
	v_accvgpr_read_b32 v97, a69
	v_accvgpr_read_b32 v96, a68
	ds_write2_b32 v0, v80, v81 offset1:1
	v_accvgpr_read_b32 v98, a70
	v_pk_mul_f32 v[80:81], v[96:97], v[72:73] op_sel_hi:[1,0]
	v_accvgpr_read_b32 v0, a24
	ds_write2_b32 v0, v80, v81 offset1:1
	v_pk_mul_f32 v[80:81], v[98:99], v[72:73] op_sel_hi:[1,0]
	v_accvgpr_read_b32 v99, a75
	v_accvgpr_read_b32 v0, a25
	v_accvgpr_read_b32 v97, a73
	v_accvgpr_read_b32 v96, a72
	ds_write2_b32 v0, v80, v81 offset1:1
	v_accvgpr_read_b32 v98, a74
	v_pk_mul_f32 v[80:81], v[96:97], v[72:73] op_sel_hi:[1,0]
	v_accvgpr_read_b32 v0, a30
	ds_write2_b32 v0, v80, v81 offset1:1
	v_pk_mul_f32 v[80:81], v[98:99], v[72:73] op_sel_hi:[1,0]
	v_accvgpr_read_b32 v0, a31
	ds_write2_b32 v0, v80, v81 offset1:1
	v_pk_mul_f32 v[80:81], v[106:107], v[72:73] op_sel_hi:[1,0]
	v_accvgpr_read_b32 v0, a32
	ds_write2_b32 v0, v80, v81 offset1:1
	v_pk_mul_f32 v[80:81], v[108:109], v[72:73] op_sel_hi:[1,0]
	v_accvgpr_read_b32 v0, a33
	ds_write2_b32 v0, v80, v81 offset1:1
	v_pk_mul_f32 v[80:81], v[110:111], v[72:73] op_sel_hi:[1,0]
	v_accvgpr_read_b32 v0, a34
	ds_write2_b32 v0, v80, v81 offset1:1
	v_pk_mul_f32 v[80:81], v[112:113], v[72:73] op_sel_hi:[1,0]
	v_accvgpr_read_b32 v0, a35
	ds_write2_b32 v0, v80, v81 offset1:1
	v_pk_mul_f32 v[80:81], v[114:115], v[72:73] op_sel_hi:[1,0]
	v_accvgpr_read_b32 v0, a40
	ds_write2_b32 v0, v80, v81 offset1:1
	v_pk_mul_f32 v[80:81], v[116:117], v[72:73] op_sel_hi:[1,0]
	v_accvgpr_read_b32 v0, a41
	ds_write2_b32 v0, v80, v81 offset1:1
	v_pk_mul_f32 v[80:81], v[118:119], v[72:73] op_sel_hi:[1,0]
	v_accvgpr_read_b32 v0, a42
	ds_write2_b32 v0, v80, v81 offset1:1
	v_pk_mul_f32 v[80:81], v[120:121], v[72:73] op_sel_hi:[1,0]
	v_accvgpr_read_b32 v0, a43
	ds_write2_b32 v0, v80, v81 offset1:1
	v_pk_mul_f32 v[80:81], v[122:123], v[72:73] op_sel_hi:[1,0]
	v_accvgpr_read_b32 v0, a44
	ds_write2_b32 v0, v80, v81 offset1:1
	v_pk_mul_f32 v[80:81], v[124:125], v[72:73] op_sel_hi:[1,0]
	v_accvgpr_read_b32 v0, a45
	ds_write2_b32 v0, v80, v81 offset1:1
	v_pk_mul_f32 v[80:81], v[66:67], v[72:73] op_sel_hi:[1,0]
	v_accvgpr_read_b32 v0, a50
	ds_write2_b32 v0, v80, v81 offset1:1
	v_pk_mul_f32 v[80:81], v[68:69], v[72:73] op_sel_hi:[1,0]
	v_accvgpr_read_b32 v0, a51
	ds_write2_b32 v0, v80, v81 offset1:1
	v_add_u32_e32 v0, s14, v84
	v_cmp_gt_i32_e32 vcc, s19, v0
	v_mov_b32_e32 v88, v73
	v_mov_b64_e32 v[80:81], v[78:79]
	s_and_saveexec_b64 s[0:1], vcc
	s_cbranch_execz .LBB0_72
	v_cmp_lt_i32_e32 vcc, s21, v0
	s_and_saveexec_b64 s[12:13], vcc
	s_xor_b64 s[12:13], exec, s[12:13]
	s_cbranch_execz .LBB0_84
	v_add_u32_e32 v66, s17, v71
	v_add_u32_e32 v0, 0xffff8000, v0
	v_and_b32_e32 v72, 0x3c0, v66
	v_add_u32_e32 v66, s15, v89
	v_lshrrev_b32_e32 v0, 9, v0
	v_and_b32_e32 v80, 0x7c0, v66
	v_readlane_b32 s24, v126, 2
	v_accvgpr_read_b32 v68, a1
	v_lshlrev_b64 v[66:67], 23, v[0:1]
	v_readlane_b32 s26, v126, 4
	v_readlane_b32 s27, v126, 5
	v_or_b32_e32 v68, v80, v68
	v_lshlrev_b32_e32 v68, 12, v68
	v_lshl_add_u64 v[66:67], s[26:27], 0, v[66:67]
	v_mov_b32_e32 v69, v1
	v_lshl_add_u64 v[66:67], v[66:67], 0, v[68:69]
	v_lshlrev_b32_e32 v68, 2, v72
	v_lshl_add_u64 v[66:67], v[66:67], 0, v[68:69]
	v_lshlrev_b64 v[68:69], 21, v[0:1]
	v_lshl_add_u64 v[68:69], s[8:9], 0, v[68:69]
	v_lshlrev_b32_e32 v0, 11, v72
	v_readlane_b32 s25, v126, 3
	v_readlane_b32 s28, v126, 6
	v_readlane_b32 s29, v126, 7
	v_readlane_b32 s30, v126, 8
	v_readlane_b32 s31, v126, 9
	v_lshl_add_u64 v[84:85], v[68:69], 0, v[0:1]

.LBB0_607:
	s_add_i32 s26, s28, s0
	s_ashr_i32 s27, s26, 31
	s_lshl_b64 s[34:35], s[26:27], 10
	v_lshlrev_b64 v[106:107], 1, v[0:1]
	s_mov_b64 s[36:37], 0x1000
	v_lshl_add_u64 v[106:107], s[34:35], 0, v[106:107]
	v_lshl_add_u64 v[80:81], s[14:15], 0, v[106:107]
	v_lshl_add_u64 v[84:85], s[6:7], 0, v[106:107]
	v_lshl_add_u64 v[88:89], s[10:11], 0, v[106:107]
	v_lshl_add_u64 v[92:93], s[8:9], 0, v[106:107]
	v_lshl_add_u64 v[96:97], s[12:13], 0, v[106:107]
	v_lshl_add_u64 v[82:83], v[80:81], 0, s[36:37]
	v_lshl_add_u64 v[86:87], v[84:85], 0, s[36:37]
	v_lshl_add_u64 v[90:91], v[88:89], 0, s[36:37]
	v_lshl_add_u64 v[94:95], v[92:93], 0, s[36:37]
	v_lshl_add_u64 v[98:99], v[96:97], 0, s[36:37]
	global_load_ushort v38, v[80:81], off
	global_load_ushort v39, v[84:85], off nt
	global_load_ushort v40, v[88:89], off nt
	global_load_ushort v41, v[92:93], off nt
	global_load_ushort v42, v[96:97], off nt
	global_load_ushort v43, v[80:81], off offset:1024
	global_load_ushort v44, v[84:85], off offset:1024 nt
	global_load_ushort v45, v[88:89], off offset:1024 nt
	global_load_ushort v46, v[92:93], off offset:1024 nt
	global_load_ushort v47, v[96:97], off offset:1024 nt
	global_load_ushort v48, v[80:81], off offset:2048
	global_load_ushort v49, v[84:85], off offset:2048 nt
	global_load_ushort v50, v[88:89], off offset:2048 nt
	global_load_ushort v51, v[92:93], off offset:2048 nt
	global_load_ushort v52, v[96:97], off offset:2048 nt
	global_load_ushort v53, v[80:81], off offset:3072
	global_load_ushort v54, v[84:85], off offset:3072 nt
	global_load_ushort v55, v[88:89], off offset:3072 nt
	global_load_ushort v56, v[92:93], off offset:3072 nt
	global_load_ushort v57, v[96:97], off offset:3072 nt
	global_load_ushort v58, v[82:83], off
	global_load_ushort v59, v[86:87], off nt
	global_load_ushort v60, v[90:91], off nt
	global_load_ushort v61, v[94:95], off nt
	global_load_ushort v62, v[98:99], off nt
	global_load_ushort v63, v[82:83], off offset:1024
	global_load_ushort v64, v[86:87], off offset:1024 nt
	global_load_ushort v65, v[90:91], off offset:1024 nt
	global_load_ushort v66, v[94:95], off offset:1024 nt
	global_load_ushort v67, v[98:99], off offset:1024 nt
	global_load_ushort v68, v[82:83], off offset:2048
	global_load_ushort v69, v[86:87], off offset:2048 nt
	global_load_ushort v70, v[90:91], off offset:2048 nt
	global_load_ushort v71, v[94:95], off offset:2048 nt
	global_load_ushort v72, v[98:99], off offset:2048 nt
	global_load_ushort v73, v[82:83], off offset:3072
	global_load_ushort v74, v[86:87], off offset:3072 nt
	global_load_ushort v75, v[90:91], off offset:3072 nt
	global_load_ushort v76, v[94:95], off offset:3072 nt
	global_load_ushort v78, v[98:99], off offset:3072 nt
	s_lshl_b64 s[34:35], s[26:27], 11
	v_lshl_add_u64 v[108:109], v[4:5], 0, s[34:35]
	s_waitcnt vmcnt(35)
	v_lshlrev_b32_e32 v100, 16, v38
	v_mul_f32_e32 v101, v100, v100
	v_fmamk_f32 v101, v101, 0xbdd2d3e8, v12
	v_mul_f32_e32 v101, v101, v100
	v_exp_f32_e32 v101, v101
	v_lshlrev_b32_e32 v102, 16, v39
	v_lshlrev_b32_e32 v103, 16, v41
	v_lshlrev_b32_e32 v104, 16, v40
	v_lshlrev_b32_e32 v105, 16, v42
	v_add_f32_e32 v101, 1.0, v101
	v_rcp_f32_e32 v101, v101
	v_pk_fma_f32 v[102:103], v[2:3], v[104:105], v[102:103]
	s_nop 0
	v_mul_f32_e32 v101, v101, v100
	v_add_f32_e32 v100, v102, v103
	v_mul_f32_e32 v100, v100, v101
	v_cvt_pk_bf16_f32 v100, v100, v13
	global_store_short v[108:109], v100, off
	s_cmp_eq_u32 s0, 0
	s_cselect_b64 s[34:35], -1, 0
	s_and_b64 s[34:35], s[24:25], s[34:35]
	s_and_b64 s[34:35], s[20:21], s[34:35]
	s_andn2_b64 vcc, exec, s[34:35]
	s_cbranch_vccnz .Lr2_nost0
	global_store_dword v[8:9], v103, off
.Lr2_nost0:
	s_waitcnt vmcnt(31)
	v_lshlrev_b32_e32 v100, 16, v43
	v_mul_f32_e32 v101, v100, v100
	v_fmamk_f32 v101, v101, 0xbdd2d3e8, v12
	v_mul_f32_e32 v101, v101, v100
	v_exp_f32_e32 v101, v101
	v_lshlrev_b32_e32 v102, 16, v44
	v_lshlrev_b32_e32 v103, 16, v46
	v_lshlrev_b32_e32 v104, 16, v45
	v_lshlrev_b32_e32 v105, 16, v47
	v_add_f32_e32 v101, 1.0, v101
	v_rcp_f32_e32 v101, v101
	v_pk_fma_f32 v[102:103], v[2:3], v[104:105], v[102:103]
	s_nop 0
	v_mul_f32_e32 v101, v101, v100
	v_add_f32_e32 v100, v102, v103
	v_mul_f32_e32 v100, v100, v101
	v_cvt_pk_bf16_f32 v100, v100, v13
	global_store_short v[108:109], v100, off offset:2048
	s_waitcnt vmcnt(27)
	v_lshlrev_b32_e32 v100, 16, v48
	v_mul_f32_e32 v101, v100, v100
	v_fmamk_f32 v101, v101, 0xbdd2d3e8, v12
	v_mul_f32_e32 v101, v101, v100
	v_exp_f32_e32 v101, v101
	v_lshlrev_b32_e32 v102, 16, v49
	v_lshlrev_b32_e32 v103, 16, v51
	v_lshlrev_b32_e32 v104, 16, v50
	v_lshlrev_b32_e32 v105, 16, v52
	v_add_f32_e32 v101, 1.0, v101
	v_rcp_f32_e32 v101, v101
	v_pk_fma_f32 v[102:103], v[2:3], v[104:105], v[102:103]
	s_nop 0
	v_mul_f32_e32 v101, v101, v100
	v_add_f32_e32 v100, v102, v103
	v_mul_f32_e32 v100, v100, v101
	v_cvt_pk_bf16_f32 v100, v100, v13
	v_lshl_add_u64 v[108:109], v[108:109], 0, s[36:37]
	global_store_short v[108:109], v100, off
	s_waitcnt vmcnt(23)
	v_lshlrev_b32_e32 v100, 16, v53
	v_mul_f32_e32 v101, v100, v100
	v_fmamk_f32 v101, v101, 0xbdd2d3e8, v12
	v_mul_f32_e32 v101, v101, v100
	v_exp_f32_e32 v101, v101
	v_lshlrev_b32_e32 v102, 16, v54
	v_lshlrev_b32_e32 v103, 16, v56
	v_lshlrev_b32_e32 v104, 16, v55
	v_lshlrev_b32_e32 v105, 16, v57
	v_add_f32_e32 v101, 1.0, v101
	v_rcp_f32_e32 v101, v101
	v_pk_fma_f32 v[102:103], v[2:3], v[104:105], v[102:103]
	s_nop 0
	v_mul_f32_e32 v101, v101, v100
	v_add_f32_e32 v100, v102, v103
	v_mul_f32_e32 v100, v100, v101
	v_cvt_pk_bf16_f32 v100, v100, v13
	global_store_short v[108:109], v100, off offset:2048
	s_waitcnt vmcnt(19)
	v_lshlrev_b32_e32 v100, 16, v58
	v_mul_f32_e32 v101, v100, v100
	v_fmamk_f32 v101, v101, 0xbdd2d3e8, v12
	v_mul_f32_e32 v101, v101, v100
	v_exp_f32_e32 v101, v101
	v_lshlrev_b32_e32 v102, 16, v59
	v_lshlrev_b32_e32 v103, 16, v61
	v_lshlrev_b32_e32 v104, 16, v60
	v_lshlrev_b32_e32 v105, 16, v62
	v_add_f32_e32 v101, 1.0, v101
	v_rcp_f32_e32 v101, v101
	v_pk_fma_f32 v[102:103], v[2:3], v[104:105], v[102:103]
	s_nop 0
	v_mul_f32_e32 v101, v101, v100
	v_add_f32_e32 v100, v102, v103
	v_mul_f32_e32 v100, v100, v101
	v_cvt_pk_bf16_f32 v100, v100, v13
	v_lshl_add_u64 v[108:109], v[108:109], 0, s[36:37]
	global_store_short v[108:109], v100, off
	s_waitcnt vmcnt(15)
	v_lshlrev_b32_e32 v100, 16, v63
	v_mul_f32_e32 v101, v100, v100
	v_fmamk_f32 v101, v101, 0xbdd2d3e8, v12
	v_mul_f32_e32 v101, v101, v100
	v_exp_f32_e32 v101, v101
	v_lshlrev_b32_e32 v102, 16, v64
	v_lshlrev_b32_e32 v103, 16, v66
	v_lshlrev_b32_e32 v104, 16, v65
	v_lshlrev_b32_e32 v105, 16, v67
	v_add_f32_e32 v101, 1.0, v101
	v_rcp_f32_e32 v101, v101
	v_pk_fma_f32 v[102:103], v[2:3], v[104:105], v[102:103]
	s_nop 0
	v_mul_f32_e32 v101, v101, v100
	v_add_f32_e32 v100, v102, v103
	v_mul_f32_e32 v100, v100, v101
	v_cvt_pk_bf16_f32 v100, v100, v13
	global_store_short v[108:109], v100, off offset:2048
	s_waitcnt vmcnt(11)
	v_lshlrev_b32_e32 v100, 16, v68
	v_mul_f32_e32 v101, v100, v100
	v_fmamk_f32 v101, v101, 0xbdd2d3e8, v12
	v_mul_f32_e32 v101, v101, v100
	v_exp_f32_e32 v101, v101
	v_lshlrev_b32_e32 v102, 16, v69
	v_lshlrev_b32_e32 v103, 16, v71
	v_lshlrev_b32_e32 v104, 16, v70
	v_lshlrev_b32_e32 v105, 16, v72
	v_add_f32_e32 v101, 1.0, v101
	v_rcp_f32_e32 v101, v101
	v_pk_fma_f32 v[102:103], v[2:3], v[104:105], v[102:103]
	s_nop 0
	v_mul_f32_e32 v101, v101, v100
	v_add_f32_e32 v100, v102, v103
	v_mul_f32_e32 v100, v100, v101
	v_cvt_pk_bf16_f32 v100, v100, v13
	v_lshl_add_u64 v[108:109], v[108:109], 0, s[36:37]
	global_store_short v[108:109], v100, off
	s_waitcnt vmcnt(7)
	v_lshlrev_b32_e32 v100, 16, v73
	v_mul_f32_e32 v101, v100, v100
	v_fmamk_f32 v101, v101, 0xbdd2d3e8, v12
	v_mul_f32_e32 v101, v101, v100
	v_exp_f32_e32 v101, v101
	v_lshlrev_b32_e32 v102, 16, v74
	v_lshlrev_b32_e32 v103, 16, v76
	v_lshlrev_b32_e32 v104, 16, v75
	v_lshlrev_b32_e32 v105, 16, v78
	v_add_f32_e32 v101, 1.0, v101
	v_rcp_f32_e32 v101, v101
	v_pk_fma_f32 v[102:103], v[2:3], v[104:105], v[102:103]
	s_nop 0
	v_mul_f32_e32 v101, v101, v100
	v_add_f32_e32 v100, v102, v103
	v_mul_f32_e32 v100, v100, v101
	v_cvt_pk_bf16_f32 v100, v100, v13
	global_store_short v[108:109], v100, off offset:2048
	s_cmp_eq_u32 s0, 56
	s_cselect_b64 s[34:35], -1, 0
	s_and_b64 s[34:35], s[22:23], s[34:35]
	s_and_b64 s[34:35], s[20:21], s[34:35]
	s_andn2_b64 vcc, exec, s[34:35]
	s_cbranch_vccnz .LBB0_606
	global_store_dword v[6:7], v102, off
	s_branch .LBB0_606

.LBB0_751:
	s_lshl_b32 s16, s15, 4
	v_add_u32_e32 v24, s16, v44
	v_ashrrev_i32_e32 v25, 31, v24
	v_lshlrev_b64 v[0:1], 11, v[24:25]
	v_lshl_add_u64 v[0:1], v[8:9], 0, v[0:1]
	global_load_dwordx2 v[2:3], v[0:1], off offset:1024
	global_load_dwordx2 v[4:5], v[0:1], off offset:1536
	global_load_dwordx2 v[26:27], v[0:1], off
	global_load_dwordx2 v[32:33], v[0:1], off offset:512
	s_add_i32 s0, s16, 0xffffe000
	s_lshr_b32 s0, s0, 11
	s_add_i32 s0, s0, 1
	s_cmpk_gt_i32 s15, 0x1ff
	s_cselect_b32 s0, s0, 0
	s_mul_hi_u32 s1, s0, 0x6000
	s_mulk_i32 s0, 0x6000
	s_add_u32 s0, s12, s0
	s_addc_u32 s1, s13, s1
	s_add_u32 s8, s0, 0x4000
	s_addc_u32 s9, s1, 0
	s_add_u32 s10, s0, 0x3000
	s_addc_u32 s11, s1, 0
	global_load_dwordx4 a[16:19], v60, s[8:9]
	global_load_dwordx4 a[20:23], v60, s[10:11]
	global_load_dwordx4 a[32:35], v61, s[8:9]
	global_load_dwordx4 a[36:39], v61, s[10:11]
	global_load_dwordx4 a[48:51], v62, s[8:9]
	global_load_dwordx4 a[52:55], v62, s[10:11]
	global_load_dwordx4 a[64:67], v63, s[8:9]
	global_load_dwordx4 a[68:71], v63, s[10:11]
	s_mov_b32 s0, 32
	v_accvgpr_write_b32 a0, 0
	v_accvgpr_mov_b32 a1, a6
	v_accvgpr_mov_b32 a2, a5
	v_accvgpr_mov_b32 a3, a4
	s_waitcnt vmcnt(11)
	v_lshlrev_b32_e32 v20, 16, v2
	v_and_b32_e32 v21, 0xffff0000, v2
	s_waitcnt vmcnt(9)
	v_lshlrev_b32_e32 v29, 16, v27
	v_lshlrev_b32_e32 v28, 16, v26
	v_and_b32_e32 v31, 0xffff0000, v27
	v_and_b32_e32 v30, 0xffff0000, v26
	s_waitcnt vmcnt(8)
	v_lshlrev_b32_e32 v27, 16, v33
	v_lshlrev_b32_e32 v26, 16, v32
	v_and_b32_e32 v33, 0xffff0000, v33
	v_and_b32_e32 v32, 0xffff0000, v32
	v_pk_add_f32 v[34:35], v[28:29], v[30:31]
	v_pk_add_f32 v[36:37], v[26:27], v[32:33]
	v_lshlrev_b32_e32 v22, 16, v3
	v_and_b32_e32 v23, 0xffff0000, v3
	v_and_b32_e32 v3, 0xffff0000, v4
	v_add_f32_e32 v2, v34, v35
	v_pk_add_f32 v[34:35], v[36:37], v[36:37] op_sel:[0,1] op_sel_hi:[1,0]
	v_lshlrev_b32_e32 v7, 16, v4
	v_lshlrev_b32_e32 v19, 16, v5
	v_and_b32_e32 v5, 0xffff0000, v5
	v_add_f32_e32 v18, v20, v21
	v_add_f32_e32 v4, v22, v23
	v_add_f32_e32 v6, 0, v2
	v_mov_b32_e32 v35, v3
	v_pk_add_f32 v[36:37], v[18:19], v[4:5]
	v_pk_add_f32 v[34:35], v[6:7], v[34:35]
	s_nop 0
	v_pk_add_f32 v[34:35], v[34:35], v[36:37]
	s_nop 0
	v_add_f32_e32 v2, v34, v35
	v_mov_b32_e32 v4, v2
	s_nop 1
	v_add_f32_dpp v4, v4, v4 quad_perm:[1,0,3,2] row_mask:0xf bank_mask:0xf
	s_nop 1
	v_add_f32_dpp v4, v4, v4 quad_perm:[2,3,0,1] row_mask:0xf bank_mask:0xf
	s_nop 1
	v_add_f32_dpp v4, v4, v4 row_half_mirror row_mask:0xf bank_mask:0xf
	s_nop 1
	v_add_f32_dpp v4, v4, v4 row_mirror row_mask:0xf bank_mask:0xf
	s_nop 0
	v_readlane_b32 s44, v4, 0
	v_readlane_b32 s45, v4, 16
	v_readlane_b32 s46, v4, 32
	v_readlane_b32 s47, v4, 48
	s_nop 1
	v_mov_b32_e32 v4, s44
	v_add_f32_e32 v4, s45, v4
	v_add_f32_e32 v4, s46, v4
	v_add_f32_e32 v4, s47, v4
	v_mov_b32_e32 v2, v4
	v_fmac_f32_e32 v30, 0xba800000, v2
	v_fmac_f32_e32 v31, 0xba800000, v2
	v_fmac_f32_e32 v29, 0xba800000, v2
	v_fmac_f32_e32 v32, 0xba800000, v2
	v_fmac_f32_e32 v33, 0xba800000, v2
	v_fmac_f32_e32 v27, 0xba800000, v2
	v_fmac_f32_e32 v28, 0xba800000, v2
	v_fmac_f32_e32 v26, 0xba800000, v2
	v_mov_b32_e32 v68, v29
	v_mov_b32_e32 v69, v31
	v_mov_b32_e32 v29, v30
	v_mov_b32_e32 v72, v27
	v_mov_b32_e32 v73, v33
	v_mov_b32_e32 v27, v32
	v_pk_mul_f32 v[30:31], v[68:69], v[68:69]
	v_pk_mul_f32 v[32:33], v[28:29], v[28:29]
	v_pk_mul_f32 v[34:35], v[72:73], v[72:73]
	v_pk_mul_f32 v[36:37], v[26:27], v[26:27]
	v_fmac_f32_e32 v20, 0xba800000, v2
	v_fmac_f32_e32 v22, 0xba800000, v2
	v_pk_mov_b32 v[74:75], v[32:33], v[30:31] op_sel:[1,0]
	v_mov_b32_e32 v33, v31
	v_pk_mov_b32 v[30:31], v[36:37], v[34:35] op_sel:[1,0]
	v_mov_b32_e32 v37, v35
	v_fmac_f32_e32 v21, 0xba800000, v2
	v_fmac_f32_e32 v23, 0xba800000, v2
	v_fmac_f32_e32 v5, 0xba800000, v2
	v_fmac_f32_e32 v19, 0xba800000, v2
	v_fmac_f32_e32 v3, 0xba800000, v2
	v_fmac_f32_e32 v7, 0xba800000, v2
	v_mul_f32_e32 v2, v20, v20
	v_mul_f32_e32 v4, v22, v22
	v_pk_add_f32 v[32:33], v[74:75], v[32:33]
	v_pk_add_f32 v[30:31], v[30:31], v[36:37]
	v_pk_fma_f32 v[38:39], v[20:21], v[20:21], v[2:3] op_sel_hi:[1,1,0]
	v_pk_fma_f32 v[70:71], v[22:23], v[22:23], v[4:5] op_sel_hi:[1,1,0]
	v_pk_add_f32 v[32:33], v[32:33], v[32:33] op_sel_hi:[0,1]
	v_pk_add_f32 v[30:31], v[30:31], v[30:31] op_sel_hi:[0,1]
	v_mul_f32_e32 v38, v7, v7
	v_mul_f32_e32 v70, v3, v3
	v_mul_f32_e32 v32, v19, v19
	v_mul_f32_e32 v30, v5, v5
	v_pk_add_f32 v[34:35], v[38:39], v[70:71]
	v_pk_add_f32 v[30:31], v[32:33], v[30:31]
	s_nop 0
	v_pk_add_f32 v[30:31], v[34:35], v[30:31]
	s_nop 0
	v_add_f32_e32 v2, v30, v31
	v_mov_b32_e32 v4, v2
	s_nop 1
	v_add_f32_dpp v4, v4, v4 quad_perm:[1,0,3,2] row_mask:0xf bank_mask:0xf
	s_nop 1
	v_add_f32_dpp v4, v4, v4 quad_perm:[2,3,0,1] row_mask:0xf bank_mask:0xf
	s_nop 1
	v_add_f32_dpp v4, v4, v4 row_half_mirror row_mask:0xf bank_mask:0xf
	s_nop 1
	v_add_f32_dpp v4, v4, v4 row_mirror row_mask:0xf bank_mask:0xf
	s_nop 0
	v_readlane_b32 s44, v4, 0
	v_readlane_b32 s45, v4, 16
	v_readlane_b32 s46, v4, 32
	v_readlane_b32 s47, v4, 48
	s_nop 1
	v_mov_b32_e32 v4, s44
	v_add_f32_e32 v4, s45, v4
	v_add_f32_e32 v4, s46, v4
	v_add_f32_e32 v4, s47, v4
	v_or_b32_e32 v30, 1, v24
	v_ashrrev_i32_e32 v31, 31, v30
	v_lshlrev_b64 v[30:31], 11, v[30:31]
	v_lshl_add_u64 v[30:31], v[8:9], 0, v[30:31]
	global_load_dwordx2 v[32:33], v[30:31], off
	global_load_dwordx2 v[34:35], v[30:31], off offset:512
	global_load_dwordx2 v[38:39], v[30:31], off offset:1024
	global_load_dwordx2 v[36:37], v[30:31], off offset:1536
	v_lshlrev_b64 v[24:25], 10, v[24:25]
	v_mov_b32_e32 v2, v4
	v_fmamk_f32 v2, v2, 0x3a800000, v59
	v_mul_f32_e32 v4, 0x4b800000, v2
	v_cmp_gt_f32_e32 vcc, s14, v2
	s_nop 1
	v_cndmask_b32_e32 v2, v2, v4, vcc
	v_rsq_f32_e32 v2, v2
	s_nop 0
	v_mul_f32_e32 v4, 0x45800000, v2
	v_cndmask_b32_e32 v6, v2, v4, vcc
	v_pk_mul_f32 v[28:29], v[28:29], v[6:7] op_sel_hi:[1,0]
	v_pk_mul_f32 v[30:31], v[68:69], v[6:7] op_sel_hi:[1,0]
	v_accvgpr_read_b32 v40, a8
	v_accvgpr_read_b32 v41, a9
	v_accvgpr_read_b32 v42, a10
	v_accvgpr_read_b32 v43, a11
	v_accvgpr_read_b32 v64, a12
	v_accvgpr_read_b32 v65, a13
	v_accvgpr_read_b32 v66, a14
	v_accvgpr_read_b32 v67, a15
	s_waitcnt vmcnt(4)
	v_pk_fma_f32 v[28:29], v[40:41], v[28:29], v[64:65]
	v_pk_fma_f32 v[68:69], v[42:43], v[30:31], v[66:67]
	v_cvt_pk_bf16_f32 v30, v28, v29
	v_mov_b32_e32 v2, 0
	v_cvt_pk_bf16_f32 v31, v68, v69
	global_store_dwordx2 v[0:1], v[30:31], off
	v_accvgpr_read_b32 v40, a16
	v_accvgpr_read_b32 v41, a17
	v_accvgpr_read_b32 v42, a18
	v_accvgpr_read_b32 v43, a19
	v_accvgpr_read_b32 v64, a20
	v_accvgpr_read_b32 v65, a21
	v_accvgpr_read_b32 v66, a22
	v_accvgpr_read_b32 v67, a23
	v_lshl_add_u64 v[30:31], v[16:17], 0, v[24:25]
	v_pk_mul_f32 v[20:21], v[20:21], v[6:7] op_sel_hi:[1,0]
	v_pk_mul_f32 v[22:23], v[22:23], v[6:7] op_sel_hi:[1,0]
	v_mov_b32_e32 v4, v19
	v_pk_mul_f32 v[4:5], v[4:5], v[6:7] op_sel_hi:[1,0]
	s_waitcnt vmcnt(1)
	v_and_b32_e32 v19, 0xffff0000, v36
	v_pk_add_f32 v[40:41], v[40:41], 1.0 op_sel_hi:[1,0]
	v_pk_add_f32 v[24:25], v[42:43], 1.0 op_sel_hi:[1,0]
	v_pk_fma_f32 v[40:41], v[40:41], v[28:29], v[64:65]
	v_pk_fma_f32 v[42:43], v[24:25], v[68:69], v[66:67]
	v_cvt_pk_fp8_f32 v2, v40, v41
	v_pk_mul_f32 v[24:25], v[26:27], v[6:7] op_sel_hi:[1,0]
	v_cvt_pk_fp8_f32 v2, v42, v43 op_sel:[0,0,1]
	global_store_dword v[30:31], v2, off
	v_accvgpr_read_b32 v64, a24
	v_accvgpr_read_b32 v65, a25
	v_accvgpr_read_b32 v66, a26
	v_accvgpr_read_b32 v67, a27
	v_accvgpr_read_b32 v68, a28
	v_accvgpr_read_b32 v69, a29
	v_accvgpr_read_b32 v70, a30
	v_accvgpr_read_b32 v71, a31
	v_pk_mul_f32 v[26:27], v[72:73], v[6:7] op_sel_hi:[1,0]
	ds_write_b128 v54, v[40:43]
	v_mov_b32_e32 v2, 0
	v_pk_fma_f32 v[28:29], v[66:67], v[26:27], v[70:71]
	v_pk_fma_f32 v[64:65], v[64:65], v[24:25], v[68:69]
	s_nop 0
	v_cvt_pk_bf16_f32 v24, v64, v65
	v_cvt_pk_bf16_f32 v25, v28, v29
	global_store_dwordx2 v[0:1], v[24:25], off offset:512
	v_accvgpr_read_b32 v24, a32
	v_accvgpr_read_b32 v25, a33
	v_accvgpr_read_b32 v26, a34
	v_accvgpr_read_b32 v27, a35
	s_nop 0
	v_accvgpr_read_b32 v40, a36
	v_accvgpr_read_b32 v41, a37
	v_accvgpr_read_b32 v42, a38
	v_accvgpr_read_b32 v43, a39
	v_pk_add_f32 v[24:25], v[24:25], 1.0 op_sel_hi:[1,0]
	v_pk_add_f32 v[26:27], v[26:27], 1.0 op_sel_hi:[1,0]
	v_pk_fma_f32 v[24:25], v[24:25], v[64:65], v[40:41]
	v_pk_fma_f32 v[26:27], v[26:27], v[28:29], v[42:43]
	v_cvt_pk_fp8_f32 v2, v24, v25
	s_nop 0
	v_cvt_pk_fp8_f32 v2, v26, v27 op_sel:[0,0,1]
	global_store_dword v[30:31], v2, off offset:256
	v_accvgpr_read_b32 v40, a40
	v_accvgpr_read_b32 v41, a41
	v_accvgpr_read_b32 v42, a42
	v_accvgpr_read_b32 v43, a43
	v_accvgpr_read_b32 v64, a44
	v_accvgpr_read_b32 v65, a45
	v_accvgpr_read_b32 v66, a46
	v_accvgpr_read_b32 v67, a47
	ds_write_b128 v54, v[24:27] offset:1024
	v_mov_b32_e32 v2, 0
	v_pk_fma_f32 v[28:29], v[22:23], v[42:43], v[66:67]
	v_pk_fma_f32 v[40:41], v[20:21], v[40:41], v[64:65]
	s_nop 0
	v_cvt_pk_bf16_f32 v20, v40, v41
	v_cvt_pk_bf16_f32 v21, v28, v29
	global_store_dwordx2 v[0:1], v[20:21], off offset:1024
	v_accvgpr_read_b32 v20, a48
	v_accvgpr_read_b32 v21, a49
	v_accvgpr_read_b32 v22, a50
	v_accvgpr_read_b32 v23, a51
	s_nop 0
	v_accvgpr_read_b32 v24, a52
	v_accvgpr_read_b32 v25, a53
	v_accvgpr_read_b32 v26, a54
	v_accvgpr_read_b32 v27, a55
	v_pk_add_f32 v[20:21], v[20:21], 1.0 op_sel_hi:[1,0]
	v_pk_add_f32 v[22:23], v[22:23], 1.0 op_sel_hi:[1,0]
	v_pk_fma_f32 v[20:21], v[40:41], v[20:21], v[24:25]
	v_pk_fma_f32 v[22:23], v[28:29], v[22:23], v[26:27]
	v_cvt_pk_fp8_f32 v2, v20, v21
	v_lshlrev_b32_e32 v26, 16, v38
	v_cvt_pk_fp8_f32 v2, v22, v23 op_sel:[0,0,1]
	global_store_dword v[30:31], v2, off offset:512
	v_accvgpr_read_b32 v64, a56
	v_accvgpr_read_b32 v65, a57
	v_accvgpr_read_b32 v66, a58
	v_accvgpr_read_b32 v67, a59
	v_accvgpr_read_b32 v68, a60
	v_accvgpr_read_b32 v69, a61
	v_accvgpr_read_b32 v70, a62
	v_accvgpr_read_b32 v71, a63
	v_mov_b32_e32 v2, v7
	v_pk_mul_f32 v[2:3], v[2:3], v[6:7] op_sel_hi:[1,0]
	ds_write_b128 v54, v[20:23] offset:2048
	v_and_b32_e32 v27, 0xffff0000, v38
	v_lshlrev_b32_e32 v28, 16, v39
	v_and_b32_e32 v29, 0xffff0000, v39
	v_lshlrev_b32_e32 v23, 16, v36
	v_lshlrev_b32_e32 v25, 16, v37
	v_and_b32_e32 v21, 0xffff0000, v37
	v_lshlrev_b32_e32 v37, 16, v33
	v_lshlrev_b32_e32 v36, 16, v32
	v_and_b32_e32 v39, 0xffff0000, v33
	v_and_b32_e32 v38, 0xffff0000, v32
	v_lshlrev_b32_e32 v33, 16, v35
	v_lshlrev_b32_e32 v32, 16, v34
	v_and_b32_e32 v35, 0xffff0000, v35
	v_and_b32_e32 v34, 0xffff0000, v34
	v_add_f32_e32 v24, v26, v27
	v_add_f32_e32 v20, v28, v29
	v_pk_fma_f32 v[40:41], v[4:5], v[66:67], v[70:71]
	v_pk_fma_f32 v[42:43], v[2:3], v[64:65], v[68:69]
	v_pk_add_f32 v[64:65], v[36:37], v[38:39]
	v_cvt_pk_bf16_f32 v2, v42, v43
	v_cvt_pk_bf16_f32 v3, v40, v41
	global_store_dwordx2 v[0:1], v[2:3], off offset:1536
	v_accvgpr_read_b32 v0, a64
	v_accvgpr_read_b32 v1, a65
	v_accvgpr_read_b32 v2, a66
	v_accvgpr_read_b32 v3, a67
	v_pk_add_f32 v[66:67], v[32:33], v[34:35]
	v_accvgpr_read_b32 v4, a68
	v_accvgpr_read_b32 v5, a69
	v_accvgpr_read_b32 v6, a70
	v_accvgpr_read_b32 v7, a71
	v_add_f32_e32 v18, v64, v65
	v_pk_add_f32 v[64:65], v[66:67], v[66:67] op_sel:[0,1] op_sel_hi:[1,0]
	v_add_f32_e32 v22, 0, v18
	v_mov_b32_e32 v65, v19
	v_pk_add_f32 v[66:67], v[24:25], v[20:21]
	v_pk_add_f32 v[64:65], v[22:23], v[64:65]
	v_mov_b32_e32 v22, 0
	v_pk_add_f32 v[64:65], v[64:65], v[66:67]
	v_pk_add_f32 v[0:1], v[0:1], 1.0 op_sel_hi:[1,0]
	v_add_f32_e32 v18, v64, v65
	ds_bpermute_b32 v20, v45, v18
	v_pk_add_f32 v[2:3], v[2:3], 1.0 op_sel_hi:[1,0]
	v_pk_fma_f32 v[64:65], v[42:43], v[0:1], v[4:5]
	v_pk_fma_f32 v[66:67], v[40:41], v[2:3], v[6:7]
	v_cvt_pk_fp8_f32 v22, v64, v65
	s_waitcnt lgkmcnt(0)
	v_add_f32_e32 v18, v18, v20
	ds_bpermute_b32 v20, v46, v18
	v_cvt_pk_fp8_f32 v22, v66, v67 op_sel:[0,0,1]
	global_store_dword v[30:31], v22, off offset:768
	v_accvgpr_read_b32 v40, a8
	v_accvgpr_read_b32 v41, a9
	v_accvgpr_read_b32 v42, a10
	v_accvgpr_read_b32 v43, a11
	v_accvgpr_read_b32 v68, a12
	v_accvgpr_read_b32 v69, a13
	v_accvgpr_read_b32 v70, a14
	v_accvgpr_read_b32 v71, a15
	ds_write_b128 v54, v[64:67] offset:3072
	s_waitcnt lgkmcnt(1)
	v_add_f32_e32 v18, v18, v20
	ds_bpermute_b32 v20, v47, v18
	s_waitcnt lgkmcnt(0)
	v_add_f32_e32 v18, v18, v20
	ds_bpermute_b32 v20, v48, v18
	s_waitcnt lgkmcnt(0)
	v_add_f32_e32 v18, v18, v20
	ds_bpermute_b32 v20, v49, v18
	s_waitcnt lgkmcnt(0)
	v_add_f32_e32 v18, v18, v20
	ds_bpermute_b32 v20, v50, v18
	s_waitcnt lgkmcnt(0)
	v_add_f32_e32 v18, v18, v20
	v_fmac_f32_e32 v38, 0xba800000, v18
	v_fmac_f32_e32 v39, 0xba800000, v18
	v_fmac_f32_e32 v37, 0xba800000, v18
	v_fmac_f32_e32 v34, 0xba800000, v18
	v_fmac_f32_e32 v35, 0xba800000, v18
	v_fmac_f32_e32 v33, 0xba800000, v18
	v_fmac_f32_e32 v36, 0xba800000, v18
	v_fmac_f32_e32 v32, 0xba800000, v18
	v_fmac_f32_e32 v26, 0xba800000, v18
	v_fmac_f32_e32 v28, 0xba800000, v18
	v_mov_b32_e32 v0, v37
	v_mov_b32_e32 v1, v39
	v_mov_b32_e32 v37, v38
	v_mov_b32_e32 v6, v33
	v_mov_b32_e32 v7, v35
	v_mov_b32_e32 v33, v34
	v_fmac_f32_e32 v27, 0xba800000, v18
	v_fmac_f32_e32 v29, 0xba800000, v18
	v_mul_f32_e32 v2, v26, v26
	v_mul_f32_e32 v4, v28, v28
	v_pk_mul_f32 v[30:31], v[0:1], v[0:1]
	v_pk_mul_f32 v[34:35], v[36:37], v[36:37]
	v_pk_mul_f32 v[38:39], v[6:7], v[6:7]
	v_pk_mul_f32 v[72:73], v[32:33], v[32:33]
	v_fmac_f32_e32 v19, 0xba800000, v18
	v_fmac_f32_e32 v23, 0xba800000, v18
	v_pk_fma_f32 v[2:3], v[26:27], v[26:27], v[2:3] op_sel_hi:[1,1,0]
	v_pk_fma_f32 v[4:5], v[28:29], v[28:29], v[4:5] op_sel_hi:[1,1,0]
	v_pk_mov_b32 v[74:75], v[34:35], v[30:31] op_sel:[1,0]
	v_mov_b32_e32 v35, v31
	v_pk_mov_b32 v[30:31], v[72:73], v[38:39] op_sel:[1,0]
	v_mov_b32_e32 v73, v39
	v_mul_f32_e32 v2, v23, v23
	v_mul_f32_e32 v4, v19, v19
	v_pk_add_f32 v[34:35], v[74:75], v[34:35]
	v_pk_add_f32 v[30:31], v[30:31], v[72:73]
	v_fmac_f32_e32 v21, 0xba800000, v18
	v_fmac_f32_e32 v25, 0xba800000, v18
	v_pk_add_f32 v[2:3], v[2:3], v[4:5]
	v_pk_add_f32 v[4:5], v[34:35], v[34:35] op_sel_hi:[0,1]
	v_pk_add_f32 v[30:31], v[30:31], v[30:31] op_sel_hi:[0,1]
	v_mul_f32_e32 v4, v25, v25
	v_mul_f32_e32 v30, v21, v21
	v_pk_add_f32 v[4:5], v[4:5], v[30:31]
	v_add_u32_e32 v30, s16, v55
	v_pk_add_f32 v[2:3], v[2:3], v[4:5]
	v_ashrrev_i32_e32 v31, 31, v30
	v_add_f32_e32 v2, v2, v3
	v_mov_b32_e32 v3, v2
	s_nop 1
	v_add_f32_dpp v3, v3, v3 quad_perm:[1,0,3,2] row_mask:0xf bank_mask:0xf
	s_nop 1
	v_add_f32_dpp v3, v3, v3 quad_perm:[2,3,0,1] row_mask:0xf bank_mask:0xf
	s_nop 1
	v_add_f32_dpp v3, v3, v3 row_half_mirror row_mask:0xf bank_mask:0xf
	s_nop 1
	v_add_f32_dpp v3, v3, v3 row_mirror row_mask:0xf bank_mask:0xf
	s_nop 0
	v_readlane_b32 s44, v3, 0
	v_readlane_b32 s45, v3, 16
	v_readlane_b32 s46, v3, 32
	v_readlane_b32 s47, v3, 48
	s_nop 1
	v_mov_b32_e32 v3, s44
	v_add_f32_e32 v3, s45, v3
	v_add_f32_e32 v3, s46, v3
	v_add_f32_e32 v3, s47, v3
	v_mov_b32_e32 v18, v23
	v_mov_b32_e32 v20, v25
	v_mov_b32_e32 v2, v3
	v_fmamk_f32 v2, v2, 0x3a800000, v59
	v_mul_f32_e32 v3, 0x4b800000, v2
	v_cmp_gt_f32_e32 vcc, s14, v2
	s_nop 1
	v_cndmask_b32_e32 v2, v2, v3, vcc
	v_rsq_f32_e32 v4, v2
	v_lshlrev_b64 v[2:3], 11, v[30:31]
	v_lshl_add_u64 v[2:3], v[8:9], 0, v[2:3]
	v_mul_f32_e32 v5, 0x45800000, v4
	v_cndmask_b32_e32 v4, v4, v5, vcc
	v_pk_mul_f32 v[34:35], v[36:37], v[4:5] op_sel_hi:[1,0]
	v_pk_mul_f32 v[0:1], v[0:1], v[4:5] op_sel_hi:[1,0]
	v_pk_fma_f32 v[64:65], v[40:41], v[34:35], v[68:69]
	v_pk_fma_f32 v[42:43], v[42:43], v[0:1], v[70:71]
	v_cvt_pk_bf16_f32 v0, v64, v65
	v_mov_b32_e32 v5, 0
	v_cvt_pk_bf16_f32 v1, v42, v43
	global_store_dwordx2 v[2:3], v[0:1], off
	v_accvgpr_read_b32 v34, a16
	v_accvgpr_read_b32 v35, a17
	v_accvgpr_read_b32 v36, a18
	v_accvgpr_read_b32 v37, a19
	v_accvgpr_read_b32 v38, a20
	v_accvgpr_read_b32 v39, a21
	v_accvgpr_read_b32 v40, a22
	v_accvgpr_read_b32 v41, a23
	v_lshlrev_b64 v[0:1], 10, v[30:31]
	v_lshl_add_u64 v[0:1], v[16:17], 0, v[0:1]
	v_pk_add_f32 v[34:35], v[34:35], 1.0 op_sel_hi:[1,0]
	v_pk_add_f32 v[30:31], v[36:37], 1.0 op_sel_hi:[1,0]
	v_pk_fma_f32 v[34:35], v[34:35], v[64:65], v[38:39]
	v_pk_fma_f32 v[36:37], v[30:31], v[42:43], v[40:41]
	v_cvt_pk_fp8_f32 v5, v34, v35
	s_nop 0
	v_cvt_pk_fp8_f32 v5, v36, v37 op_sel:[0,0,1]
	global_store_dword v[0:1], v5, off
	v_accvgpr_read_b32 v38, a24
	v_accvgpr_read_b32 v39, a25
	v_accvgpr_read_b32 v40, a26
	v_accvgpr_read_b32 v41, a27
	v_accvgpr_read_b32 v64, a28
	v_accvgpr_read_b32 v65, a29
	v_accvgpr_read_b32 v66, a30
	v_accvgpr_read_b32 v67, a31
	v_pk_mul_f32 v[30:31], v[32:33], v[4:5] op_sel_hi:[1,0]
	v_pk_mul_f32 v[6:7], v[6:7], v[4:5] op_sel_hi:[1,0]
	ds_write_b128 v56, v[34:37]
	v_mov_b32_e32 v5, 0
	v_pk_fma_f32 v[6:7], v[40:41], v[6:7], v[66:67]
	v_pk_fma_f32 v[38:39], v[38:39], v[30:31], v[64:65]
	s_nop 0
	v_cvt_pk_bf16_f32 v30, v38, v39
	v_cvt_pk_bf16_f32 v31, v6, v7
	global_store_dwordx2 v[2:3], v[30:31], off offset:512
	v_accvgpr_read_b32 v30, a32
	v_accvgpr_read_b32 v31, a33
	v_accvgpr_read_b32 v32, a34
	v_accvgpr_read_b32 v33, a35
	s_nop 0
	v_accvgpr_read_b32 v34, a36
	v_accvgpr_read_b32 v35, a37
	v_accvgpr_read_b32 v36, a38
	v_accvgpr_read_b32 v37, a39
	v_pk_add_f32 v[30:31], v[30:31], 1.0 op_sel_hi:[1,0]
	v_pk_add_f32 v[32:33], v[32:33], 1.0 op_sel_hi:[1,0]
	v_pk_fma_f32 v[30:31], v[30:31], v[38:39], v[34:35]
	v_pk_fma_f32 v[32:33], v[32:33], v[6:7], v[36:37]
	v_cvt_pk_fp8_f32 v5, v30, v31
	s_nop 0
	v_cvt_pk_fp8_f32 v5, v32, v33 op_sel:[0,0,1]
	global_store_dword v[0:1], v5, off offset:256
	v_accvgpr_read_b32 v34, a40
	v_accvgpr_read_b32 v35, a41
	v_accvgpr_read_b32 v36, a42
	v_accvgpr_read_b32 v37, a43
	v_accvgpr_read_b32 v38, a44
	v_accvgpr_read_b32 v39, a45
	v_accvgpr_read_b32 v40, a46
	v_accvgpr_read_b32 v41, a47
	v_pk_mul_f32 v[6:7], v[26:27], v[4:5] op_sel_hi:[1,0]
	v_pk_mul_f32 v[26:27], v[28:29], v[4:5] op_sel_hi:[1,0]
	ds_write_b128 v56, v[30:33] offset:1024
	v_mov_b32_e32 v5, 0
	v_pk_fma_f32 v[36:37], v[26:27], v[36:37], v[40:41]
	v_pk_fma_f32 v[6:7], v[6:7], v[34:35], v[38:39]
	s_nop 0
	v_cvt_pk_bf16_f32 v26, v6, v7
	v_cvt_pk_bf16_f32 v27, v36, v37
	global_store_dwordx2 v[2:3], v[26:27], off offset:1024
	v_accvgpr_read_b32 v26, a48
	v_accvgpr_read_b32 v27, a49
	v_accvgpr_read_b32 v28, a50
	v_accvgpr_read_b32 v29, a51
	s_nop 0
	v_accvgpr_read_b32 v30, a52
	v_accvgpr_read_b32 v31, a53
	v_accvgpr_read_b32 v32, a54
	v_accvgpr_read_b32 v33, a55
	v_pk_add_f32 v[26:27], v[26:27], 1.0 op_sel_hi:[1,0]
	v_pk_add_f32 v[28:29], v[28:29], 1.0 op_sel_hi:[1,0]
	v_pk_fma_f32 v[26:27], v[6:7], v[26:27], v[30:31]
	v_pk_fma_f32 v[28:29], v[36:37], v[28:29], v[32:33]
	v_cvt_pk_fp8_f32 v5, v26, v27
	s_nop 0
	v_cvt_pk_fp8_f32 v5, v28, v29 op_sel:[0,0,1]
	global_store_dword v[0:1], v5, off offset:512
	v_accvgpr_read_b32 v30, a56
	v_accvgpr_read_b32 v31, a57
	v_accvgpr_read_b32 v32, a58
	v_accvgpr_read_b32 v33, a59
	v_accvgpr_read_b32 v34, a60
	v_accvgpr_read_b32 v35, a61
	v_accvgpr_read_b32 v36, a62
	v_accvgpr_read_b32 v37, a63
	v_pk_mul_f32 v[6:7], v[18:19], v[4:5] op_sel_hi:[1,0]
	v_pk_mul_f32 v[4:5], v[20:21], v[4:5] op_sel_hi:[1,0]
	ds_write_b128 v56, v[26:29] offset:2048
	v_mov_b32_e32 v26, 0
	v_pk_fma_f32 v[22:23], v[4:5], v[32:33], v[36:37]
	v_pk_fma_f32 v[24:25], v[6:7], v[30:31], v[34:35]
	s_nop 0
	v_cvt_pk_bf16_f32 v4, v24, v25
	v_cvt_pk_bf16_f32 v5, v22, v23
	global_store_dwordx2 v[2:3], v[4:5], off offset:1536
	v_accvgpr_read_b32 v4, a64
	v_accvgpr_read_b32 v5, a65
	v_accvgpr_read_b32 v6, a66
	v_accvgpr_read_b32 v7, a67
	s_nop 0
	v_accvgpr_read_b32 v18, a68
	v_accvgpr_read_b32 v19, a69
	v_accvgpr_read_b32 v20, a70
	v_accvgpr_read_b32 v21, a71
	v_mov_b32_e32 v2, v58
	v_mov_b32_e32 v3, v57
	v_pk_add_f32 v[6:7], v[6:7], 1.0 op_sel_hi:[1,0]
	v_pk_add_f32 v[4:5], v[4:5], 1.0 op_sel_hi:[1,0]
	v_pk_fma_f32 v[6:7], v[22:23], v[6:7], v[20:21]
	v_pk_fma_f32 v[4:5], v[24:25], v[4:5], v[18:19]
	s_nop 0
	v_cvt_pk_fp8_f32 v26, v4, v5
	s_nop 0
	v_cvt_pk_fp8_f32 v26, v6, v7 op_sel:[0,0,1]
	ds_write_b128 v56, v[4:7] offset:3072
	global_store_dword v[0:1], v26, off offset:768
	s_waitcnt lgkmcnt(0)
	s_barrier

.LBB0_1049:
	v_add_u32_e32 v5, 0xffffe000, v22
	v_lshrrev_b32_e32 v5, 11, v5
	v_add_u32_e32 v5, 1, v5
	s_and_b64 s[0:1], exec, vcc
	v_cndmask_b32_e64 v21, 0, v5, s[4:5]
	v_mov_b64_e32 v[48:49], s[20:21]
	s_or_b64 s[12:13], s[0:1], s[12:13]
	v_mad_u64_u32 v[50:51], s[0:1], v21, s27, v[48:49]
	v_lshl_add_u64 v[74:75], v[50:51], 0, s[14:15]
	v_mov_b32_e32 v5, v1
	v_lshl_add_u64 v[50:51], v[74:75], 0, v[0:1]
	v_lshl_add_u64 v[70:71], v[74:75], 0, v[4:5]
	v_mov_b32_e32 v7, v1
	v_mov_b32_e32 v9, v1
	global_load_dwordx4 v[50:53], v[50:51], off
	s_nop 0
	global_load_dwordx4 v[70:73], v[70:71], off
	v_lshl_add_u64 v[78:79], v[74:75], 0, v[6:7]
	v_lshl_add_u64 v[74:75], v[74:75], 0, v[8:9]
	global_load_dwordx4 v[78:81], v[78:79], off
	v_lshlrev_b32_e32 v86, 16, v28
	global_load_dwordx4 v[82:85], v[74:75], off
	v_lshlrev_b32_e32 v74, 16, v30
	v_and_b32_e32 v75, 0xffff0000, v30
	v_lshlrev_b32_e32 v30, 16, v31
	v_and_b32_e32 v31, 0xffff0000, v31
	v_and_b32_e32 v87, 0xffff0000, v28
	v_lshlrev_b32_e32 v28, 16, v29
	v_and_b32_e32 v29, 0xffff0000, v29
	v_lshlrev_b32_e32 v88, 16, v26
	v_and_b32_e32 v89, 0xffff0000, v26
	v_lshlrev_b32_e32 v26, 16, v27
	v_and_b32_e32 v27, 0xffff0000, v27
	v_lshlrev_b32_e32 v90, 16, v24
	v_and_b32_e32 v91, 0xffff0000, v24
	v_lshlrev_b32_e32 v24, 16, v25
	v_and_b32_e32 v25, 0xffff0000, v25
	v_add_u32_e32 v21, 5, v21
	s_waitcnt vmcnt(3)
	v_pk_mul_f32 v[46:47], v[46:47], v[52:53]
	v_pk_mul_f32 v[44:45], v[44:45], v[50:51]
	s_waitcnt vmcnt(2)
	v_pk_mul_f32 v[42:43], v[42:43], v[72:73]
	v_pk_mul_f32 v[40:41], v[40:41], v[70:71]
	s_waitcnt vmcnt(1)
	v_pk_mul_f32 v[50:51], v[38:39], v[80:81]
	v_pk_mul_f32 v[52:53], v[36:37], v[78:79]
	s_waitcnt vmcnt(0)
	v_pk_mul_f32 v[70:71], v[32:33], v[84:85]
	v_pk_mul_f32 v[72:73], v[34:35], v[82:83]
	v_pk_fma_f32 v[36:37], v[74:75], s[16:17], v[44:45] op_sel_hi:[1,0,1]
	v_pk_fma_f32 v[38:39], v[30:31], s[16:17], v[46:47] op_sel_hi:[1,0,1]
	v_pk_fma_f32 v[32:33], v[86:87], s[16:17], v[40:41] op_sel_hi:[1,0,1]
	v_pk_fma_f32 v[34:35], v[28:29], s[16:17], v[42:43] op_sel_hi:[1,0,1]
	v_pk_mov_b32 v[40:41], v[36:37], v[38:39] op_sel:[1,0]
	v_mov_b32_e32 v42, v36
	v_mov_b32_e32 v43, v39
	v_pk_mov_b32 v[44:45], v[32:33], v[34:35] op_sel:[1,0]
	v_mov_b32_e32 v46, v32
	v_mov_b32_e32 v47, v35
	v_pk_add_f32 v[40:41], v[40:41], v[42:43]
	v_pk_add_f32 v[42:43], v[44:45], v[46:47]
	v_pk_fma_f32 v[28:29], v[26:27], s[16:17], v[50:51] op_sel_hi:[1,0,1]
	v_pk_fma_f32 v[30:31], v[88:89], s[16:17], v[52:53] op_sel_hi:[1,0,1]
	v_pk_fma_f32 v[24:25], v[24:25], s[16:17], v[70:71] op_sel_hi:[1,0,1]
	v_pk_fma_f32 v[26:27], v[90:91], s[16:17], v[72:73] op_sel_hi:[1,0,1]
	v_add_f32_e32 v23, v40, v41
	v_pk_add_f32 v[40:41], v[42:43], v[42:43] op_sel:[0,1] op_sel_hi:[1,0]
	v_add_f32_e32 v50, v30, v31
	v_add_f32_e32 v52, v28, v29
	v_mov_b32_e32 v71, v26
	v_mov_b32_e32 v51, v24
	v_mov_b32_e32 v53, v25
	v_add_f32_e32 v70, 0, v23
	v_mov_b32_e32 v41, v27
	v_pk_add_f32 v[44:45], v[50:51], v[52:53]
	v_pk_add_f32 v[40:41], v[70:71], v[40:41]
	global_load_dwordx4 v[50:53], v[16:17], off
	global_load_dwordx4 v[70:73], v[18:19], off
	v_pk_add_f32 v[40:41], v[40:41], v[44:45]
	s_nop 0
	v_add_f32_e32 v23, v40, v41
	v_mov_b32_e32 v40, v23
	s_nop 1
	v_add_f32_dpp v40, v40, v40 quad_perm:[1,0,3,2] row_mask:0xf bank_mask:0xf
	s_nop 1
	v_add_f32_dpp v40, v40, v40 quad_perm:[2,3,0,1] row_mask:0xf bank_mask:0xf
	s_nop 1
	v_add_f32_dpp v40, v40, v40 row_half_mirror row_mask:0xf bank_mask:0xf
	s_nop 1
	v_add_f32_dpp v40, v40, v40 row_mirror row_mask:0xf bank_mask:0xf
	s_nop 0
	v_readlane_b32 s44, v40, 0
	v_readlane_b32 s45, v40, 16
	v_readlane_b32 s46, v40, 32
	v_readlane_b32 s47, v40, 48
	s_nop 1
	v_mov_b32_e32 v40, s44
	v_add_f32_e32 v40, s45, v40
	v_add_f32_e32 v40, s46, v40
	v_add_f32_e32 v40, s47, v40
	v_mov_b32_e32 v23, v40
	v_fmamk_f32 v37, v23, 0xba800000, v37
	v_fmac_f32_e32 v36, 0xba800000, v23
	v_fmamk_f32 v39, v23, 0xba800000, v39
	v_fmac_f32_e32 v38, 0xba800000, v23
	v_fmamk_f32 v33, v23, 0xba800000, v33
	v_fmac_f32_e32 v32, 0xba800000, v23
	v_fmamk_f32 v35, v23, 0xba800000, v35
	v_fmac_f32_e32 v34, 0xba800000, v23
	v_pk_mul_f32 v[40:41], v[38:39], v[38:39]
	v_pk_mul_f32 v[42:43], v[36:37], v[36:37]
	v_pk_mul_f32 v[44:45], v[34:35], v[34:35]
	v_pk_mul_f32 v[46:47], v[32:33], v[32:33]
	v_fmac_f32_e32 v30, 0xba800000, v23
	v_fmac_f32_e32 v28, 0xba800000, v23
	v_pk_mov_b32 v[78:79], v[42:43], v[40:41] op_sel:[1,0]
	v_mov_b32_e32 v43, v41
	v_pk_mov_b32 v[40:41], v[46:47], v[44:45] op_sel:[1,0]
	v_mov_b32_e32 v47, v45
	v_fmamk_f32 v31, v23, 0xba800000, v31
	v_fmamk_f32 v29, v23, 0xba800000, v29
	v_mul_f32_e32 v74, v30, v30
	v_mul_f32_e32 v76, v28, v28
	v_pk_add_f32 v[42:43], v[78:79], v[42:43]
	v_pk_add_f32 v[40:41], v[40:41], v[46:47]
	v_fmamk_f32 v25, v23, 0xba800000, v25
	v_fmac_f32_e32 v24, 0xba800000, v23
	v_fmamk_f32 v27, v23, 0xba800000, v27
	v_fmac_f32_e32 v26, 0xba800000, v23
	v_pk_fma_f32 v[44:45], v[30:31], v[30:31], v[74:75] op_sel_hi:[1,1,0]
	v_pk_fma_f32 v[74:75], v[28:29], v[28:29], v[76:77] op_sel_hi:[1,1,0]
	v_pk_add_f32 v[42:43], v[42:43], v[42:43] op_sel_hi:[0,1]
	v_pk_add_f32 v[40:41], v[40:41], v[40:41] op_sel_hi:[0,1]
	v_mul_f32_e32 v44, v26, v26
	v_mul_f32_e32 v74, v27, v27
	v_mul_f32_e32 v42, v24, v24
	v_mul_f32_e32 v40, v25, v25
	v_pk_add_f32 v[44:45], v[44:45], v[74:75]
	v_pk_add_f32 v[40:41], v[42:43], v[40:41]
	v_mad_u64_u32 v[74:75], s[0:1], v21, s27, v[48:49]
	v_pk_add_f32 v[40:41], v[44:45], v[40:41]
	v_lshl_add_u64 v[42:43], v[74:75], 0, s[18:19]
	v_add_f32_e32 v23, v40, v41
	v_mov_b32_e32 v40, v23
	s_nop 1
	v_add_f32_dpp v40, v40, v40 quad_perm:[1,0,3,2] row_mask:0xf bank_mask:0xf
	s_nop 1
	v_add_f32_dpp v40, v40, v40 quad_perm:[2,3,0,1] row_mask:0xf bank_mask:0xf
	s_nop 1
	v_add_f32_dpp v40, v40, v40 row_half_mirror row_mask:0xf bank_mask:0xf
	s_nop 1
	v_add_f32_dpp v40, v40, v40 row_mirror row_mask:0xf bank_mask:0xf
	s_nop 0
	v_readlane_b32 s44, v40, 0
	v_readlane_b32 s45, v40, 16
	v_readlane_b32 s46, v40, 32
	v_readlane_b32 s47, v40, 48
	s_nop 1
	v_mov_b32_e32 v40, s44
	v_add_f32_e32 v40, s45, v40
	v_add_f32_e32 v40, s46, v40
	v_add_f32_e32 v40, s47, v40
	v_lshl_add_u64 v[46:47], v[42:43], 0, v[0:1]
	v_ashrrev_i32_e32 v23, 31, v22
	v_lshlrev_b64 v[22:23], 11, v[22:23]
	v_mov_b32_e32 v21, v40
	v_fmamk_f32 v21, v21, 0x3a800000, v54
	v_mul_f32_e32 v40, 0x4b800000, v21
	v_cmp_gt_f32_e32 vcc, s28, v21
	s_nop 1
	v_cndmask_b32_e32 v21, v21, v40, vcc
	v_rsq_f32_e32 v21, v21
	v_lshl_add_u64 v[40:41], v[2:3], 0, v[22:23]
	v_lshl_add_u64 v[22:23], v[14:15], 0, v[22:23]
	v_mul_f32_e32 v44, 0x45800000, v21
	v_cndmask_b32_e32 v44, v21, v44, vcc
	v_pk_mul_f32 v[36:37], v[36:37], v[44:45] op_sel_hi:[1,0]
	v_pk_mul_f32 v[38:39], v[38:39], v[44:45] op_sel_hi:[1,0]
	s_waitcnt vmcnt(0)
	v_pk_fma_f32 v[70:71], v[50:51], v[36:37], v[70:71]
	v_pk_fma_f32 v[38:39], v[52:53], v[38:39], v[72:73]
	v_cvt_pk_bf16_f32 v36, v70, v71
	v_pk_mul_f32 v[32:33], v[32:33], v[44:45] op_sel_hi:[1,0]
	v_cvt_pk_bf16_f32 v37, v38, v39
	global_store_dwordx2 v[40:41], v[36:37], off
	global_load_dwordx4 v[46:49], v[46:47], off
	v_lshl_add_u64 v[36:37], v[74:75], 0, v[0:1]
	global_load_dwordx4 v[50:53], v[36:37], off
	v_pk_mul_f32 v[34:35], v[34:35], v[44:45] op_sel_hi:[1,0]
	v_pk_mul_f32 v[30:31], v[30:31], v[44:45] op_sel_hi:[1,0]
	v_pk_mul_f32 v[28:29], v[28:29], v[44:45] op_sel_hi:[1,0]
	v_pk_mul_f32 v[26:27], v[26:27], v[44:45] op_sel_hi:[1,0]
	v_pk_mul_f32 v[24:25], v[24:25], v[44:45] op_sel_hi:[1,0]
	s_waitcnt vmcnt(1)
	v_pk_add_f32 v[46:47], v[46:47], 1.0 op_sel_hi:[1,0]
	v_pk_add_f32 v[48:49], v[48:49], 1.0 op_sel_hi:[1,0]
	s_waitcnt vmcnt(0)
	v_pk_fma_f32 v[46:47], v[46:47], v[70:71], v[50:51]
	v_pk_fma_f32 v[38:39], v[48:49], v[38:39], v[52:53]
	v_cvt_pk_bf16_f32 v46, v46, v47
	s_nop 0
	v_cvt_pk_bf16_f32 v47, v38, v39
	global_store_dwordx2 v[22:23], v[46:47], off
	global_load_dwordx4 v[46:49], v[16:17], off offset:1024
	s_nop 0
	global_load_dwordx4 v[50:53], v[18:19], off offset:1024
	v_lshl_add_u64 v[38:39], v[42:43], 0, v[4:5]
	v_mov_b32_e32 v5, v61
	s_waitcnt vmcnt(0)
	v_pk_fma_f32 v[52:53], v[48:49], v[34:35], v[52:53]
	v_pk_fma_f32 v[50:51], v[46:47], v[32:33], v[50:51]
	s_nop 0
	v_cvt_pk_bf16_f32 v32, v50, v51
	v_cvt_pk_bf16_f32 v33, v52, v53
	global_store_dwordx2 v[40:41], v[32:33], off offset:512
	global_load_dwordx4 v[32:35], v[38:39], off
	s_nop 0
	global_load_dwordx4 v[46:49], v[36:37], off offset:1024
	v_lshl_add_u64 v[38:39], v[42:43], 0, v[6:7]
	s_waitcnt vmcnt(1)
	v_pk_add_f32 v[32:33], v[32:33], 1.0 op_sel_hi:[1,0]
	v_pk_add_f32 v[34:35], v[34:35], 1.0 op_sel_hi:[1,0]
	s_waitcnt vmcnt(0)
	v_pk_fma_f32 v[32:33], v[32:33], v[50:51], v[46:47]
	v_pk_fma_f32 v[34:35], v[34:35], v[52:53], v[48:49]
	v_cvt_pk_bf16_f32 v32, v32, v33
	s_nop 0
	v_cvt_pk_bf16_f32 v33, v34, v35
	global_store_dwordx2 v[22:23], v[32:33], off offset:512
	global_load_dwordx4 v[32:35], v[16:17], off offset:2048
	s_nop 0
	global_load_dwordx4 v[46:49], v[18:19], off offset:2048
	s_waitcnt vmcnt(0)
	v_pk_fma_f32 v[48:49], v[34:35], v[28:29], v[48:49]
	v_pk_fma_f32 v[46:47], v[32:33], v[30:31], v[46:47]
	s_nop 0
	v_cvt_pk_bf16_f32 v28, v46, v47
	v_cvt_pk_bf16_f32 v29, v48, v49
	global_store_dwordx2 v[40:41], v[28:29], off offset:1024
	global_load_dwordx4 v[28:31], v[38:39], off
	s_nop 0
	global_load_dwordx4 v[32:35], v[36:37], off offset:2048
	v_lshl_add_u64 v[38:39], v[42:43], 0, v[8:9]
	s_waitcnt vmcnt(1)
	v_pk_add_f32 v[28:29], v[28:29], 1.0 op_sel_hi:[1,0]
	v_pk_add_f32 v[30:31], v[30:31], 1.0 op_sel_hi:[1,0]
	s_waitcnt vmcnt(0)
	v_pk_fma_f32 v[28:29], v[28:29], v[46:47], v[32:33]
	v_pk_fma_f32 v[30:31], v[30:31], v[48:49], v[34:35]
	v_cvt_pk_bf16_f32 v28, v28, v29
	s_nop 0
	v_cvt_pk_bf16_f32 v29, v30, v31
	global_store_dwordx2 v[22:23], v[28:29], off offset:1024
	global_load_dwordx4 v[28:31], v[16:17], off offset:3072
	s_nop 0
	global_load_dwordx4 v[32:35], v[18:19], off offset:3072
	s_waitcnt vmcnt(0)
	v_pk_fma_f32 v[42:43], v[24:25], v[30:31], v[34:35]
	v_pk_fma_f32 v[44:45], v[26:27], v[28:29], v[32:33]
	v_mov_b64_e32 v[30:31], v[62:63]
	v_cvt_pk_bf16_f32 v24, v44, v45
	v_cvt_pk_bf16_f32 v25, v42, v43
	global_store_dwordx2 v[40:41], v[24:25], off offset:1536
	global_load_dwordx4 v[32:35], v[38:39], off
	s_nop 0
	global_load_dwordx4 v[36:39], v[36:37], off offset:3072
	v_mov_b64_e32 v[28:29], v[64:65]
	v_mov_b64_e32 v[26:27], v[66:67]
	v_mov_b64_e32 v[24:25], v[68:69]
	s_waitcnt vmcnt(1)
	v_pk_add_f32 v[32:33], v[32:33], 1.0 op_sel_hi:[1,0]
	v_pk_add_f32 v[34:35], v[34:35], 1.0 op_sel_hi:[1,0]
	s_waitcnt vmcnt(0)
	v_pk_fma_f32 v[32:33], v[44:45], v[32:33], v[36:37]
	v_pk_fma_f32 v[34:35], v[42:43], v[34:35], v[38:39]
	v_cvt_pk_bf16_f32 v32, v32, v33
	s_nop 0
	v_cvt_pk_bf16_f32 v33, v34, v35
	global_store_dwordx2 v[22:23], v[32:33], off offset:1536
	v_mov_b32_e32 v22, v20
	s_andn2_b64 exec, exec, s[12:13]
	s_cbranch_execz .LBB0_1055

.LBB0_1352:
	s_lshl_b32 s16, s15, 4
	v_add_u32_e32 v36, s16, v56
	v_ashrrev_i32_e32 v37, 31, v36
	v_lshlrev_b64 v[0:1], 11, v[36:37]
	v_lshl_add_u64 v[0:1], v[8:9], 0, v[0:1]
	global_load_dwordx2 v[2:3], v[0:1], off offset:1024
	global_load_dwordx2 v[4:5], v[0:1], off offset:1536
	global_load_dwordx2 v[38:39], v[0:1], off
	global_load_dwordx2 v[44:45], v[0:1], off offset:512
	s_add_i32 s0, s16, 0xffffe000
	s_lshr_b32 s0, s0, 11
	s_add_i32 s0, s0, 6
	s_cmpk_gt_i32 s15, 0x1ff
	s_cselect_b32 s0, s0, 5
	s_mul_hi_u32 s1, s0, 0x6000
	s_mulk_i32 s0, 0x6000
	s_add_u32 s0, s12, s0
	s_addc_u32 s1, s13, s1
	s_add_u32 s10, s0, 0x4000
	s_addc_u32 s11, s1, 0
	s_add_u32 s8, s0, 0x3000
	s_addc_u32 s9, s1, 0
	global_load_dwordx4 a[16:19], v72, s[10:11]
	global_load_dwordx4 a[20:23], v72, s[8:9]
	global_load_dwordx4 a[32:35], v73, s[10:11]
	global_load_dwordx4 a[36:39], v73, s[8:9]
	global_load_dwordx4 a[48:51], v74, s[10:11]
	global_load_dwordx4 a[52:55], v74, s[8:9]
	global_load_dwordx4 a[64:67], v75, s[10:11]
	global_load_dwordx4 a[68:71], v75, s[8:9]
	s_mov_b32 s0, 32
	v_accvgpr_write_b32 a0, 0
	v_accvgpr_mov_b32 a1, a6
	v_accvgpr_mov_b32 a2, a5
	v_accvgpr_mov_b32 a3, a4
	s_waitcnt vmcnt(11)
	v_lshlrev_b32_e32 v32, 16, v2
	v_and_b32_e32 v33, 0xffff0000, v2
	s_waitcnt vmcnt(9)
	v_lshlrev_b32_e32 v41, 16, v39
	v_lshlrev_b32_e32 v40, 16, v38
	v_and_b32_e32 v43, 0xffff0000, v39
	v_and_b32_e32 v42, 0xffff0000, v38
	s_waitcnt vmcnt(8)
	v_lshlrev_b32_e32 v39, 16, v45
	v_lshlrev_b32_e32 v38, 16, v44
	v_and_b32_e32 v45, 0xffff0000, v45
	v_and_b32_e32 v44, 0xffff0000, v44
	v_pk_add_f32 v[46:47], v[40:41], v[42:43]
	v_pk_add_f32 v[48:49], v[38:39], v[44:45]
	v_lshlrev_b32_e32 v34, 16, v3
	v_and_b32_e32 v35, 0xffff0000, v3
	v_and_b32_e32 v3, 0xffff0000, v4
	v_add_f32_e32 v2, v46, v47
	v_pk_add_f32 v[46:47], v[48:49], v[48:49] op_sel:[0,1] op_sel_hi:[1,0]
	v_lshlrev_b32_e32 v7, 16, v4
	v_lshlrev_b32_e32 v31, 16, v5
	v_and_b32_e32 v5, 0xffff0000, v5
	v_add_f32_e32 v30, v32, v33
	v_add_f32_e32 v4, v34, v35
	v_add_f32_e32 v6, 0, v2
	v_mov_b32_e32 v47, v3
	v_pk_add_f32 v[48:49], v[30:31], v[4:5]
	v_pk_add_f32 v[46:47], v[6:7], v[46:47]
	s_nop 0
	v_pk_add_f32 v[46:47], v[46:47], v[48:49]
	s_nop 0
	v_add_f32_e32 v2, v46, v47
	v_mov_b32_e32 v4, v2
	s_nop 1
	v_add_f32_dpp v4, v4, v4 quad_perm:[1,0,3,2] row_mask:0xf bank_mask:0xf
	s_nop 1
	v_add_f32_dpp v4, v4, v4 quad_perm:[2,3,0,1] row_mask:0xf bank_mask:0xf
	s_nop 1
	v_add_f32_dpp v4, v4, v4 row_half_mirror row_mask:0xf bank_mask:0xf
	s_nop 1
	v_add_f32_dpp v4, v4, v4 row_mirror row_mask:0xf bank_mask:0xf
	s_nop 0
	v_readlane_b32 s44, v4, 0
	v_readlane_b32 s45, v4, 16
	v_readlane_b32 s46, v4, 32
	v_readlane_b32 s47, v4, 48
	s_nop 1
	v_mov_b32_e32 v4, s44
	v_add_f32_e32 v4, s45, v4
	v_add_f32_e32 v4, s46, v4
	v_add_f32_e32 v4, s47, v4
	v_mov_b32_e32 v2, v4
	v_fmac_f32_e32 v42, 0xba800000, v2
	v_fmac_f32_e32 v43, 0xba800000, v2
	v_fmac_f32_e32 v41, 0xba800000, v2
	v_fmac_f32_e32 v44, 0xba800000, v2
	v_fmac_f32_e32 v45, 0xba800000, v2
	v_fmac_f32_e32 v39, 0xba800000, v2
	v_fmac_f32_e32 v40, 0xba800000, v2
	v_fmac_f32_e32 v38, 0xba800000, v2
	v_mov_b32_e32 v82, v41
	v_mov_b32_e32 v83, v43
	v_mov_b32_e32 v41, v42
	v_mov_b32_e32 v86, v39
	v_mov_b32_e32 v87, v45
	v_mov_b32_e32 v39, v44
	v_pk_mul_f32 v[42:43], v[82:83], v[82:83]
	v_pk_mul_f32 v[44:45], v[40:41], v[40:41]
	v_pk_mul_f32 v[46:47], v[86:87], v[86:87]
	v_pk_mul_f32 v[48:49], v[38:39], v[38:39]
	v_fmac_f32_e32 v32, 0xba800000, v2
	v_fmac_f32_e32 v34, 0xba800000, v2
	v_pk_mov_b32 v[88:89], v[44:45], v[42:43] op_sel:[1,0]
	v_mov_b32_e32 v45, v43
	v_pk_mov_b32 v[42:43], v[48:49], v[46:47] op_sel:[1,0]
	v_mov_b32_e32 v49, v47
	v_fmac_f32_e32 v33, 0xba800000, v2
	v_fmac_f32_e32 v35, 0xba800000, v2
	v_fmac_f32_e32 v5, 0xba800000, v2
	v_fmac_f32_e32 v31, 0xba800000, v2
	v_fmac_f32_e32 v3, 0xba800000, v2
	v_fmac_f32_e32 v7, 0xba800000, v2
	v_mul_f32_e32 v2, v32, v32
	v_mul_f32_e32 v4, v34, v34
	v_pk_add_f32 v[44:45], v[88:89], v[44:45]
	v_pk_add_f32 v[42:43], v[42:43], v[48:49]
	v_pk_fma_f32 v[50:51], v[32:33], v[32:33], v[2:3] op_sel_hi:[1,1,0]
	v_pk_fma_f32 v[84:85], v[34:35], v[34:35], v[4:5] op_sel_hi:[1,1,0]
	v_pk_add_f32 v[44:45], v[44:45], v[44:45] op_sel_hi:[0,1]
	v_pk_add_f32 v[42:43], v[42:43], v[42:43] op_sel_hi:[0,1]
	v_mul_f32_e32 v50, v7, v7
	v_mul_f32_e32 v84, v3, v3
	v_mul_f32_e32 v44, v31, v31
	v_mul_f32_e32 v42, v5, v5
	v_pk_add_f32 v[46:47], v[50:51], v[84:85]
	v_pk_add_f32 v[42:43], v[44:45], v[42:43]
	s_nop 0
	v_pk_add_f32 v[42:43], v[46:47], v[42:43]
	s_nop 0
	v_add_f32_e32 v2, v42, v43
	v_mov_b32_e32 v4, v2
	s_nop 1
	v_add_f32_dpp v4, v4, v4 quad_perm:[1,0,3,2] row_mask:0xf bank_mask:0xf
	s_nop 1
	v_add_f32_dpp v4, v4, v4 quad_perm:[2,3,0,1] row_mask:0xf bank_mask:0xf
	s_nop 1
	v_add_f32_dpp v4, v4, v4 row_half_mirror row_mask:0xf bank_mask:0xf
	s_nop 1
	v_add_f32_dpp v4, v4, v4 row_mirror row_mask:0xf bank_mask:0xf
	s_nop 0
	v_readlane_b32 s44, v4, 0
	v_readlane_b32 s45, v4, 16
	v_readlane_b32 s46, v4, 32
	v_readlane_b32 s47, v4, 48
	s_nop 1
	v_mov_b32_e32 v4, s44
	v_add_f32_e32 v4, s45, v4
	v_add_f32_e32 v4, s46, v4
	v_add_f32_e32 v4, s47, v4
	v_or_b32_e32 v42, 1, v36
	v_ashrrev_i32_e32 v43, 31, v42
	v_lshlrev_b64 v[42:43], 11, v[42:43]
	v_lshl_add_u64 v[42:43], v[8:9], 0, v[42:43]
	global_load_dwordx2 v[44:45], v[42:43], off
	global_load_dwordx2 v[46:47], v[42:43], off offset:512
	global_load_dwordx2 v[50:51], v[42:43], off offset:1024
	global_load_dwordx2 v[48:49], v[42:43], off offset:1536
	v_lshlrev_b64 v[36:37], 10, v[36:37]
	v_mov_b32_e32 v2, v4
	v_fmamk_f32 v2, v2, 0x3a800000, v71
	v_mul_f32_e32 v4, 0x4b800000, v2
	v_cmp_gt_f32_e32 vcc, s14, v2
	s_nop 1
	v_cndmask_b32_e32 v2, v2, v4, vcc
	v_rsq_f32_e32 v2, v2
	s_nop 0
	v_mul_f32_e32 v4, 0x45800000, v2
	v_cndmask_b32_e32 v6, v2, v4, vcc
	v_pk_mul_f32 v[40:41], v[40:41], v[6:7] op_sel_hi:[1,0]
	v_pk_mul_f32 v[42:43], v[82:83], v[6:7] op_sel_hi:[1,0]
	v_accvgpr_read_b32 v52, a8
	v_accvgpr_read_b32 v53, a9
	v_accvgpr_read_b32 v54, a10
	v_accvgpr_read_b32 v55, a11
	v_accvgpr_read_b32 v78, a12
	v_accvgpr_read_b32 v79, a13
	v_accvgpr_read_b32 v80, a14
	v_accvgpr_read_b32 v81, a15
	s_waitcnt vmcnt(4)
	v_pk_fma_f32 v[40:41], v[52:53], v[40:41], v[78:79]
	v_pk_fma_f32 v[82:83], v[54:55], v[42:43], v[80:81]
	v_cvt_pk_bf16_f32 v42, v40, v41
	v_mov_b32_e32 v2, 0
	v_cvt_pk_bf16_f32 v43, v82, v83
	global_store_dwordx2 v[0:1], v[42:43], off
	v_accvgpr_read_b32 v52, a16
	v_accvgpr_read_b32 v53, a17
	v_accvgpr_read_b32 v54, a18
	v_accvgpr_read_b32 v55, a19
	v_accvgpr_read_b32 v78, a20
	v_accvgpr_read_b32 v79, a21
	v_accvgpr_read_b32 v80, a22
	v_accvgpr_read_b32 v81, a23
	v_lshl_add_u64 v[42:43], v[28:29], 0, v[36:37]
	v_pk_mul_f32 v[32:33], v[32:33], v[6:7] op_sel_hi:[1,0]
	v_pk_mul_f32 v[34:35], v[34:35], v[6:7] op_sel_hi:[1,0]
	v_mov_b32_e32 v4, v31
	v_pk_mul_f32 v[4:5], v[4:5], v[6:7] op_sel_hi:[1,0]
	s_waitcnt vmcnt(1)
	v_and_b32_e32 v31, 0xffff0000, v48
	v_pk_add_f32 v[52:53], v[52:53], 1.0 op_sel_hi:[1,0]
	v_pk_add_f32 v[36:37], v[54:55], 1.0 op_sel_hi:[1,0]
	v_pk_fma_f32 v[52:53], v[52:53], v[40:41], v[78:79]
	v_pk_fma_f32 v[54:55], v[36:37], v[82:83], v[80:81]
	v_cvt_pk_fp8_f32 v2, v52, v53
	v_pk_mul_f32 v[36:37], v[38:39], v[6:7] op_sel_hi:[1,0]
	v_cvt_pk_fp8_f32 v2, v54, v55 op_sel:[0,0,1]
	global_store_dword v[42:43], v2, off
	v_accvgpr_read_b32 v78, a24
	v_accvgpr_read_b32 v79, a25
	v_accvgpr_read_b32 v80, a26
	v_accvgpr_read_b32 v81, a27
	v_accvgpr_read_b32 v82, a28
	v_accvgpr_read_b32 v83, a29
	v_accvgpr_read_b32 v84, a30
	v_accvgpr_read_b32 v85, a31
	v_pk_mul_f32 v[38:39], v[86:87], v[6:7] op_sel_hi:[1,0]
	ds_write_b128 v66, v[52:55]
	v_mov_b32_e32 v2, 0
	v_pk_fma_f32 v[40:41], v[80:81], v[38:39], v[84:85]
	v_pk_fma_f32 v[78:79], v[78:79], v[36:37], v[82:83]
	s_nop 0
	v_cvt_pk_bf16_f32 v36, v78, v79
	v_cvt_pk_bf16_f32 v37, v40, v41
	global_store_dwordx2 v[0:1], v[36:37], off offset:512
	v_accvgpr_read_b32 v36, a32
	v_accvgpr_read_b32 v37, a33
	v_accvgpr_read_b32 v38, a34
	v_accvgpr_read_b32 v39, a35
	s_nop 0
	v_accvgpr_read_b32 v52, a36
	v_accvgpr_read_b32 v53, a37
	v_accvgpr_read_b32 v54, a38
	v_accvgpr_read_b32 v55, a39
	v_pk_add_f32 v[36:37], v[36:37], 1.0 op_sel_hi:[1,0]
	v_pk_add_f32 v[38:39], v[38:39], 1.0 op_sel_hi:[1,0]
	v_pk_fma_f32 v[36:37], v[36:37], v[78:79], v[52:53]
	v_pk_fma_f32 v[38:39], v[38:39], v[40:41], v[54:55]
	v_cvt_pk_fp8_f32 v2, v36, v37
	s_nop 0
	v_cvt_pk_fp8_f32 v2, v38, v39 op_sel:[0,0,1]
	global_store_dword v[42:43], v2, off offset:256
	v_accvgpr_read_b32 v52, a40
	v_accvgpr_read_b32 v53, a41
	v_accvgpr_read_b32 v54, a42
	v_accvgpr_read_b32 v55, a43
	v_accvgpr_read_b32 v78, a44
	v_accvgpr_read_b32 v79, a45
	v_accvgpr_read_b32 v80, a46
	v_accvgpr_read_b32 v81, a47
	ds_write_b128 v66, v[36:39] offset:1024
	v_mov_b32_e32 v2, 0
	v_pk_fma_f32 v[40:41], v[34:35], v[54:55], v[80:81]
	v_pk_fma_f32 v[52:53], v[32:33], v[52:53], v[78:79]
	s_nop 0
	v_cvt_pk_bf16_f32 v32, v52, v53
	v_cvt_pk_bf16_f32 v33, v40, v41
	global_store_dwordx2 v[0:1], v[32:33], off offset:1024
	v_accvgpr_read_b32 v32, a48
	v_accvgpr_read_b32 v33, a49
	v_accvgpr_read_b32 v34, a50
	v_accvgpr_read_b32 v35, a51
	s_nop 0
	v_accvgpr_read_b32 v36, a52
	v_accvgpr_read_b32 v37, a53
	v_accvgpr_read_b32 v38, a54
	v_accvgpr_read_b32 v39, a55
	v_pk_add_f32 v[32:33], v[32:33], 1.0 op_sel_hi:[1,0]
	v_pk_add_f32 v[34:35], v[34:35], 1.0 op_sel_hi:[1,0]
	v_pk_fma_f32 v[32:33], v[52:53], v[32:33], v[36:37]
	v_pk_fma_f32 v[34:35], v[40:41], v[34:35], v[38:39]
	v_cvt_pk_fp8_f32 v2, v32, v33
	v_lshlrev_b32_e32 v38, 16, v50
	v_cvt_pk_fp8_f32 v2, v34, v35 op_sel:[0,0,1]
	global_store_dword v[42:43], v2, off offset:512
	v_accvgpr_read_b32 v78, a56
	v_accvgpr_read_b32 v79, a57
	v_accvgpr_read_b32 v80, a58
	v_accvgpr_read_b32 v81, a59
	v_accvgpr_read_b32 v82, a60
	v_accvgpr_read_b32 v83, a61
	v_accvgpr_read_b32 v84, a62
	v_accvgpr_read_b32 v85, a63
	v_mov_b32_e32 v2, v7
	v_pk_mul_f32 v[2:3], v[2:3], v[6:7] op_sel_hi:[1,0]
	ds_write_b128 v66, v[32:35] offset:2048
	v_and_b32_e32 v39, 0xffff0000, v50
	v_lshlrev_b32_e32 v40, 16, v51
	v_and_b32_e32 v41, 0xffff0000, v51
	v_lshlrev_b32_e32 v35, 16, v48
	v_lshlrev_b32_e32 v37, 16, v49
	v_and_b32_e32 v33, 0xffff0000, v49
	v_lshlrev_b32_e32 v49, 16, v45
	v_lshlrev_b32_e32 v48, 16, v44
	v_and_b32_e32 v51, 0xffff0000, v45
	v_and_b32_e32 v50, 0xffff0000, v44
	v_lshlrev_b32_e32 v45, 16, v47
	v_lshlrev_b32_e32 v44, 16, v46
	v_and_b32_e32 v47, 0xffff0000, v47
	v_and_b32_e32 v46, 0xffff0000, v46
	v_add_f32_e32 v36, v38, v39
	v_add_f32_e32 v32, v40, v41
	v_pk_fma_f32 v[52:53], v[4:5], v[80:81], v[84:85]
	v_pk_fma_f32 v[54:55], v[2:3], v[78:79], v[82:83]
	v_pk_add_f32 v[78:79], v[48:49], v[50:51]
	v_cvt_pk_bf16_f32 v2, v54, v55
	v_cvt_pk_bf16_f32 v3, v52, v53
	global_store_dwordx2 v[0:1], v[2:3], off offset:1536
	v_accvgpr_read_b32 v0, a64
	v_accvgpr_read_b32 v1, a65
	v_accvgpr_read_b32 v2, a66
	v_accvgpr_read_b32 v3, a67
	v_pk_add_f32 v[80:81], v[44:45], v[46:47]
	v_accvgpr_read_b32 v4, a68
	v_accvgpr_read_b32 v5, a69
	v_accvgpr_read_b32 v6, a70
	v_accvgpr_read_b32 v7, a71
	v_add_f32_e32 v30, v78, v79
	v_pk_add_f32 v[78:79], v[80:81], v[80:81] op_sel:[0,1] op_sel_hi:[1,0]
	v_add_f32_e32 v34, 0, v30
	v_mov_b32_e32 v79, v31
	v_pk_add_f32 v[80:81], v[36:37], v[32:33]
	v_pk_add_f32 v[78:79], v[34:35], v[78:79]
	v_mov_b32_e32 v34, 0
	v_pk_add_f32 v[78:79], v[78:79], v[80:81]
	v_pk_add_f32 v[0:1], v[0:1], 1.0 op_sel_hi:[1,0]
	v_add_f32_e32 v30, v78, v79
	ds_bpermute_b32 v32, v57, v30
	v_pk_add_f32 v[2:3], v[2:3], 1.0 op_sel_hi:[1,0]
	v_pk_fma_f32 v[78:79], v[54:55], v[0:1], v[4:5]
	v_pk_fma_f32 v[80:81], v[52:53], v[2:3], v[6:7]
	v_cvt_pk_fp8_f32 v34, v78, v79
	s_waitcnt lgkmcnt(0)
	v_add_f32_e32 v30, v30, v32
	ds_bpermute_b32 v32, v58, v30
	v_cvt_pk_fp8_f32 v34, v80, v81 op_sel:[0,0,1]
	global_store_dword v[42:43], v34, off offset:768
	v_accvgpr_read_b32 v52, a8
	v_accvgpr_read_b32 v53, a9
	v_accvgpr_read_b32 v54, a10
	v_accvgpr_read_b32 v55, a11
	v_accvgpr_read_b32 v82, a12
	v_accvgpr_read_b32 v83, a13
	v_accvgpr_read_b32 v84, a14
	v_accvgpr_read_b32 v85, a15
	ds_write_b128 v66, v[78:81] offset:3072
	s_waitcnt lgkmcnt(1)
	v_add_f32_e32 v30, v30, v32
	ds_bpermute_b32 v32, v59, v30
	s_waitcnt lgkmcnt(0)
	v_add_f32_e32 v30, v30, v32
	ds_bpermute_b32 v32, v60, v30
	s_waitcnt lgkmcnt(0)
	v_add_f32_e32 v30, v30, v32
	ds_bpermute_b32 v32, v61, v30
	s_waitcnt lgkmcnt(0)
	v_add_f32_e32 v30, v30, v32
	ds_bpermute_b32 v32, v62, v30
	s_waitcnt lgkmcnt(0)
	v_add_f32_e32 v30, v30, v32
	v_fmac_f32_e32 v50, 0xba800000, v30
	v_fmac_f32_e32 v51, 0xba800000, v30
	v_fmac_f32_e32 v49, 0xba800000, v30
	v_fmac_f32_e32 v46, 0xba800000, v30
	v_fmac_f32_e32 v47, 0xba800000, v30
	v_fmac_f32_e32 v45, 0xba800000, v30
	v_fmac_f32_e32 v48, 0xba800000, v30
	v_fmac_f32_e32 v44, 0xba800000, v30
	v_fmac_f32_e32 v38, 0xba800000, v30
	v_fmac_f32_e32 v40, 0xba800000, v30
	v_mov_b32_e32 v0, v49
	v_mov_b32_e32 v1, v51
	v_mov_b32_e32 v49, v50
	v_mov_b32_e32 v6, v45
	v_mov_b32_e32 v7, v47
	v_mov_b32_e32 v45, v46
	v_fmac_f32_e32 v39, 0xba800000, v30
	v_fmac_f32_e32 v41, 0xba800000, v30
	v_mul_f32_e32 v2, v38, v38
	v_mul_f32_e32 v4, v40, v40
	v_pk_mul_f32 v[42:43], v[0:1], v[0:1]
	v_pk_mul_f32 v[46:47], v[48:49], v[48:49]
	v_pk_mul_f32 v[50:51], v[6:7], v[6:7]
	v_pk_mul_f32 v[86:87], v[44:45], v[44:45]
	v_fmac_f32_e32 v31, 0xba800000, v30
	v_fmac_f32_e32 v35, 0xba800000, v30
	v_pk_fma_f32 v[2:3], v[38:39], v[38:39], v[2:3] op_sel_hi:[1,1,0]
	v_pk_fma_f32 v[4:5], v[40:41], v[40:41], v[4:5] op_sel_hi:[1,1,0]
	v_pk_mov_b32 v[88:89], v[46:47], v[42:43] op_sel:[1,0]
	v_mov_b32_e32 v47, v43
	v_pk_mov_b32 v[42:43], v[86:87], v[50:51] op_sel:[1,0]
	v_mov_b32_e32 v87, v51
	v_mul_f32_e32 v2, v35, v35
	v_mul_f32_e32 v4, v31, v31
	v_pk_add_f32 v[46:47], v[88:89], v[46:47]
	v_pk_add_f32 v[42:43], v[42:43], v[86:87]
	v_fmac_f32_e32 v33, 0xba800000, v30
	v_fmac_f32_e32 v37, 0xba800000, v30
	v_pk_add_f32 v[2:3], v[2:3], v[4:5]
	v_pk_add_f32 v[4:5], v[46:47], v[46:47] op_sel_hi:[0,1]
	v_pk_add_f32 v[42:43], v[42:43], v[42:43] op_sel_hi:[0,1]
	v_mul_f32_e32 v4, v37, v37
	v_mul_f32_e32 v42, v33, v33
	v_pk_add_f32 v[4:5], v[4:5], v[42:43]
	v_add_u32_e32 v42, s16, v67
	v_pk_add_f32 v[2:3], v[2:3], v[4:5]
	v_ashrrev_i32_e32 v43, 31, v42
	v_add_f32_e32 v2, v2, v3
	v_mov_b32_e32 v3, v2
	s_nop 1
	v_add_f32_dpp v3, v3, v3 quad_perm:[1,0,3,2] row_mask:0xf bank_mask:0xf
	s_nop 1
	v_add_f32_dpp v3, v3, v3 quad_perm:[2,3,0,1] row_mask:0xf bank_mask:0xf
	s_nop 1
	v_add_f32_dpp v3, v3, v3 row_half_mirror row_mask:0xf bank_mask:0xf
	s_nop 1
	v_add_f32_dpp v3, v3, v3 row_mirror row_mask:0xf bank_mask:0xf
	s_nop 0
	v_readlane_b32 s44, v3, 0
	v_readlane_b32 s45, v3, 16
	v_readlane_b32 s46, v3, 32
	v_readlane_b32 s47, v3, 48
	s_nop 1
	v_mov_b32_e32 v3, s44
	v_add_f32_e32 v3, s45, v3
	v_add_f32_e32 v3, s46, v3
	v_add_f32_e32 v3, s47, v3
	v_mov_b32_e32 v30, v35
	v_mov_b32_e32 v32, v37
	v_mov_b32_e32 v2, v3
	v_fmamk_f32 v2, v2, 0x3a800000, v71
	v_mul_f32_e32 v3, 0x4b800000, v2
	v_cmp_gt_f32_e32 vcc, s14, v2
	s_nop 1
	v_cndmask_b32_e32 v2, v2, v3, vcc
	v_rsq_f32_e32 v4, v2
	v_lshlrev_b64 v[2:3], 11, v[42:43]
	v_lshl_add_u64 v[2:3], v[8:9], 0, v[2:3]
	v_mul_f32_e32 v5, 0x45800000, v4
	v_cndmask_b32_e32 v4, v4, v5, vcc
	v_pk_mul_f32 v[46:47], v[48:49], v[4:5] op_sel_hi:[1,0]
	v_pk_mul_f32 v[0:1], v[0:1], v[4:5] op_sel_hi:[1,0]
	v_pk_fma_f32 v[78:79], v[52:53], v[46:47], v[82:83]
	v_pk_fma_f32 v[54:55], v[54:55], v[0:1], v[84:85]
	v_cvt_pk_bf16_f32 v0, v78, v79
	v_mov_b32_e32 v5, 0
	v_cvt_pk_bf16_f32 v1, v54, v55
	global_store_dwordx2 v[2:3], v[0:1], off
	v_accvgpr_read_b32 v46, a16
	v_accvgpr_read_b32 v47, a17
	v_accvgpr_read_b32 v48, a18
	v_accvgpr_read_b32 v49, a19
	v_accvgpr_read_b32 v50, a20
	v_accvgpr_read_b32 v51, a21
	v_accvgpr_read_b32 v52, a22
	v_accvgpr_read_b32 v53, a23
	v_lshlrev_b64 v[0:1], 10, v[42:43]
	v_lshl_add_u64 v[0:1], v[28:29], 0, v[0:1]
	v_pk_add_f32 v[46:47], v[46:47], 1.0 op_sel_hi:[1,0]
	v_pk_add_f32 v[42:43], v[48:49], 1.0 op_sel_hi:[1,0]
	v_pk_fma_f32 v[46:47], v[46:47], v[78:79], v[50:51]
	v_pk_fma_f32 v[48:49], v[42:43], v[54:55], v[52:53]
	v_cvt_pk_fp8_f32 v5, v46, v47
	s_nop 0
	v_cvt_pk_fp8_f32 v5, v48, v49 op_sel:[0,0,1]
	global_store_dword v[0:1], v5, off
	v_accvgpr_read_b32 v50, a24
	v_accvgpr_read_b32 v51, a25
	v_accvgpr_read_b32 v52, a26
	v_accvgpr_read_b32 v53, a27
	v_accvgpr_read_b32 v78, a28
	v_accvgpr_read_b32 v79, a29
	v_accvgpr_read_b32 v80, a30
	v_accvgpr_read_b32 v81, a31
	v_pk_mul_f32 v[42:43], v[44:45], v[4:5] op_sel_hi:[1,0]
	v_pk_mul_f32 v[6:7], v[6:7], v[4:5] op_sel_hi:[1,0]
	ds_write_b128 v68, v[46:49]
	v_mov_b32_e32 v5, 0
	v_pk_fma_f32 v[6:7], v[52:53], v[6:7], v[80:81]
	v_pk_fma_f32 v[50:51], v[50:51], v[42:43], v[78:79]
	s_nop 0
	v_cvt_pk_bf16_f32 v42, v50, v51
	v_cvt_pk_bf16_f32 v43, v6, v7
	global_store_dwordx2 v[2:3], v[42:43], off offset:512
	v_accvgpr_read_b32 v42, a32
	v_accvgpr_read_b32 v43, a33
	v_accvgpr_read_b32 v44, a34
	v_accvgpr_read_b32 v45, a35
	s_nop 0
	v_accvgpr_read_b32 v46, a36
	v_accvgpr_read_b32 v47, a37
	v_accvgpr_read_b32 v48, a38
	v_accvgpr_read_b32 v49, a39
	v_pk_add_f32 v[42:43], v[42:43], 1.0 op_sel_hi:[1,0]
	v_pk_add_f32 v[44:45], v[44:45], 1.0 op_sel_hi:[1,0]
	v_pk_fma_f32 v[42:43], v[42:43], v[50:51], v[46:47]
	v_pk_fma_f32 v[44:45], v[44:45], v[6:7], v[48:49]
	v_cvt_pk_fp8_f32 v5, v42, v43
	s_nop 0
	v_cvt_pk_fp8_f32 v5, v44, v45 op_sel:[0,0,1]
	global_store_dword v[0:1], v5, off offset:256
	v_accvgpr_read_b32 v46, a40
	v_accvgpr_read_b32 v47, a41
	v_accvgpr_read_b32 v48, a42
	v_accvgpr_read_b32 v49, a43
	v_accvgpr_read_b32 v50, a44
	v_accvgpr_read_b32 v51, a45
	v_accvgpr_read_b32 v52, a46
	v_accvgpr_read_b32 v53, a47
	v_pk_mul_f32 v[6:7], v[38:39], v[4:5] op_sel_hi:[1,0]
	v_pk_mul_f32 v[38:39], v[40:41], v[4:5] op_sel_hi:[1,0]
	ds_write_b128 v68, v[42:45] offset:1024
	v_mov_b32_e32 v5, 0
	v_pk_fma_f32 v[48:49], v[38:39], v[48:49], v[52:53]
	v_pk_fma_f32 v[6:7], v[6:7], v[46:47], v[50:51]
	s_nop 0
	v_cvt_pk_bf16_f32 v38, v6, v7
	v_cvt_pk_bf16_f32 v39, v48, v49
	global_store_dwordx2 v[2:3], v[38:39], off offset:1024
	v_accvgpr_read_b32 v38, a48
	v_accvgpr_read_b32 v39, a49
	v_accvgpr_read_b32 v40, a50
	v_accvgpr_read_b32 v41, a51
	s_nop 0
	v_accvgpr_read_b32 v42, a52
	v_accvgpr_read_b32 v43, a53
	v_accvgpr_read_b32 v44, a54
	v_accvgpr_read_b32 v45, a55
	v_pk_add_f32 v[38:39], v[38:39], 1.0 op_sel_hi:[1,0]
	v_pk_add_f32 v[40:41], v[40:41], 1.0 op_sel_hi:[1,0]
	v_pk_fma_f32 v[38:39], v[6:7], v[38:39], v[42:43]
	v_pk_fma_f32 v[40:41], v[48:49], v[40:41], v[44:45]
	v_cvt_pk_fp8_f32 v5, v38, v39
	s_nop 0
	v_cvt_pk_fp8_f32 v5, v40, v41 op_sel:[0,0,1]
	global_store_dword v[0:1], v5, off offset:512
	v_accvgpr_read_b32 v42, a56
	v_accvgpr_read_b32 v43, a57
	v_accvgpr_read_b32 v44, a58
	v_accvgpr_read_b32 v45, a59
	v_accvgpr_read_b32 v46, a60
	v_accvgpr_read_b32 v47, a61
	v_accvgpr_read_b32 v48, a62
	v_accvgpr_read_b32 v49, a63
	v_pk_mul_f32 v[6:7], v[30:31], v[4:5] op_sel_hi:[1,0]
	v_pk_mul_f32 v[4:5], v[32:33], v[4:5] op_sel_hi:[1,0]
	ds_write_b128 v68, v[38:41] offset:2048
	v_mov_b32_e32 v38, 0
	v_pk_fma_f32 v[34:35], v[4:5], v[44:45], v[48:49]
	v_pk_fma_f32 v[36:37], v[6:7], v[42:43], v[46:47]
	s_nop 0
	v_cvt_pk_bf16_f32 v4, v36, v37
	v_cvt_pk_bf16_f32 v5, v34, v35
	global_store_dwordx2 v[2:3], v[4:5], off offset:1536
	v_accvgpr_read_b32 v4, a64
	v_accvgpr_read_b32 v5, a65
	v_accvgpr_read_b32 v6, a66
	v_accvgpr_read_b32 v7, a67
	s_nop 0
	v_accvgpr_read_b32 v30, a68
	v_accvgpr_read_b32 v31, a69
	v_accvgpr_read_b32 v32, a70
	v_accvgpr_read_b32 v33, a71
	v_mov_b32_e32 v2, v70
	v_mov_b32_e32 v3, v69
	v_pk_add_f32 v[6:7], v[6:7], 1.0 op_sel_hi:[1,0]
	v_pk_add_f32 v[4:5], v[4:5], 1.0 op_sel_hi:[1,0]
	v_pk_fma_f32 v[6:7], v[34:35], v[6:7], v[32:33]
	v_pk_fma_f32 v[4:5], v[36:37], v[4:5], v[30:31]
	s_nop 0
	v_cvt_pk_fp8_f32 v38, v4, v5
	s_nop 0
	v_cvt_pk_fp8_f32 v38, v6, v7 op_sel:[0,0,1]
	ds_write_b128 v68, v[4:7] offset:3072
	global_store_dword v[0:1], v38, off offset:768
	s_waitcnt lgkmcnt(0)
	s_barrier

.LBB0_1650:
	v_add_u32_e32 v9, 0xffffe000, v8
	v_lshrrev_b32_e32 v9, 11, v9
	v_readlane_b32 s24, v126, 2
	v_add_u32_e32 v9, 6, v9
	v_readlane_b32 s30, v126, 8
	v_readlane_b32 s31, v126, 9
	v_cndmask_b32_e64 v9, 5, v9, s[0:1]
	v_mov_b32_e32 v29, v1
	v_mov_b64_e32 v[62:63], s[30:31]
	v_mad_u64_u32 v[62:63], s[0:1], v9, s22, v[62:63]
	v_lshl_add_u64 v[88:89], v[62:63], 0, s[10:11]
	v_lshl_add_u64 v[62:63], v[88:89], 0, v[0:1]
	v_lshl_add_u64 v[80:81], v[88:89], 0, v[28:29]
	v_mov_b32_e32 v31, v1
	global_load_dwordx4 v[62:65], v[62:63], off
	s_nop 0
	global_load_dwordx4 v[80:83], v[80:81], off
	v_lshl_add_u64 v[84:85], v[88:89], 0, v[30:31]
	global_load_dwordx4 v[84:87], v[84:85], off
	v_mov_b32_e32 v33, v1
	v_lshl_add_u64 v[88:89], v[88:89], 0, v[32:33]
	global_load_dwordx4 v[88:91], v[88:89], off
	v_lshlrev_b32_e32 v92, 16, v42
	v_and_b32_e32 v93, 0xffff0000, v42
	v_lshlrev_b32_e32 v42, 16, v43
	v_and_b32_e32 v43, 0xffff0000, v43
	v_lshlrev_b32_e32 v94, 16, v40
	v_and_b32_e32 v95, 0xffff0000, v40
	v_lshlrev_b32_e32 v96, 16, v41
	v_and_b32_e32 v97, 0xffff0000, v41
	v_lshlrev_b32_e32 v100, 16, v36
	v_and_b32_e32 v101, 0xffff0000, v36
	v_lshlrev_b32_e32 v102, 16, v37
	v_and_b32_e32 v103, 0xffff0000, v37
	v_lshlrev_b32_e32 v98, 16, v38
	v_and_b32_e32 v99, 0xffff0000, v38
	v_lshlrev_b32_e32 v38, 16, v39
	v_and_b32_e32 v39, 0xffff0000, v39
	s_and_b64 s[14:15], exec, vcc
	s_or_b64 s[8:9], s[14:15], s[8:9]
	v_readlane_b32 s25, v126, 3
	v_readlane_b32 s26, v126, 4
	v_readlane_b32 s27, v126, 5
	v_readlane_b32 s28, v126, 6
	v_readlane_b32 s29, v126, 7
	s_waitcnt vmcnt(3)
	v_pk_mul_f32 v[36:37], v[58:59], v[64:65]
	v_pk_mul_f32 v[40:41], v[56:57], v[62:63]
	s_waitcnt vmcnt(2)
	v_pk_mul_f32 v[54:55], v[54:55], v[82:83]
	v_pk_mul_f32 v[52:53], v[52:53], v[80:81]
	s_waitcnt vmcnt(1)
	v_pk_mul_f32 v[56:57], v[50:51], v[86:87]
	v_pk_mul_f32 v[58:59], v[48:49], v[84:85]
	v_pk_fma_f32 v[48:49], v[92:93], s[12:13], v[40:41] op_sel_hi:[1,0,1]
	v_pk_fma_f32 v[50:51], v[42:43], s[12:13], v[36:37] op_sel_hi:[1,0,1]
	v_pk_fma_f32 v[40:41], v[94:95], s[12:13], v[52:53] op_sel_hi:[1,0,1]
	v_pk_fma_f32 v[42:43], v[96:97], s[12:13], v[54:55] op_sel_hi:[1,0,1]
	v_pk_fma_f32 v[38:39], v[38:39], s[12:13], v[56:57] op_sel_hi:[1,0,1]
	v_pk_fma_f32 v[36:37], v[98:99], s[12:13], v[58:59] op_sel_hi:[1,0,1]
	v_pk_mov_b32 v[52:53], v[48:49], v[50:51] op_sel:[1,0]
	v_mov_b32_e32 v54, v48
	v_mov_b32_e32 v55, v51
	v_pk_mov_b32 v[56:57], v[40:41], v[42:43] op_sel:[1,0]
	v_mov_b32_e32 v58, v40
	v_mov_b32_e32 v59, v43
	s_waitcnt vmcnt(0)
	v_pk_mul_f32 v[44:45], v[44:45], v[90:91]
	v_pk_mul_f32 v[46:47], v[46:47], v[88:89]
	v_pk_add_f32 v[52:53], v[52:53], v[54:55]
	v_pk_add_f32 v[54:55], v[56:57], v[58:59]
	v_pk_fma_f32 v[44:45], v[102:103], s[12:13], v[44:45] op_sel_hi:[1,0,1]
	v_pk_fma_f32 v[46:47], v[100:101], s[12:13], v[46:47] op_sel_hi:[1,0,1]
	v_add_f32_e32 v9, v52, v53
	v_pk_add_f32 v[52:53], v[54:55], v[54:55] op_sel:[0,1] op_sel_hi:[1,0]
	v_add_f32_e32 v62, v36, v37
	v_add_f32_e32 v64, v38, v39
	v_mov_b32_e32 v81, v46
	v_mov_b32_e32 v63, v44
	v_mov_b32_e32 v65, v45
	v_add_f32_e32 v80, 0, v9
	v_mov_b32_e32 v53, v47
	v_pk_add_f32 v[56:57], v[62:63], v[64:65]
	v_pk_add_f32 v[52:53], v[80:81], v[52:53]
	s_nop 0
	v_pk_add_f32 v[52:53], v[52:53], v[56:57]
	s_nop 0
	v_add_f32_e32 v9, v52, v53
	v_mov_b32_e32 v29, v9
	s_nop 1
	v_add_f32_dpp v29, v29, v29 quad_perm:[1,0,3,2] row_mask:0xf bank_mask:0xf
	s_nop 1
	v_add_f32_dpp v29, v29, v29 quad_perm:[2,3,0,1] row_mask:0xf bank_mask:0xf
	s_nop 1
	v_add_f32_dpp v29, v29, v29 row_half_mirror row_mask:0xf bank_mask:0xf
	s_nop 1
	v_add_f32_dpp v29, v29, v29 row_mirror row_mask:0xf bank_mask:0xf
	s_nop 0
	v_readlane_b32 s44, v29, 0
	v_readlane_b32 s45, v29, 16
	v_readlane_b32 s46, v29, 32
	v_readlane_b32 s47, v29, 48
	s_nop 1
	v_mov_b32_e32 v29, s44
	v_add_f32_e32 v29, s45, v29
	v_add_f32_e32 v29, s46, v29
	v_add_f32_e32 v29, s47, v29
	global_load_dwordx4 v[52:55], v[10:11], off
	global_load_dwordx4 v[56:59], v[12:13], off
	v_mov_b32_e32 v9, v29
	v_fmamk_f32 v49, v9, 0xba800000, v49
	v_fmac_f32_e32 v48, 0xba800000, v9
	v_fmamk_f32 v51, v9, 0xba800000, v51
	v_fmac_f32_e32 v50, 0xba800000, v9
	v_fmamk_f32 v41, v9, 0xba800000, v41
	v_fmac_f32_e32 v40, 0xba800000, v9
	v_fmamk_f32 v43, v9, 0xba800000, v43
	v_fmac_f32_e32 v42, 0xba800000, v9
	v_pk_mul_f32 v[62:63], v[50:51], v[50:51]
	v_pk_mul_f32 v[64:65], v[48:49], v[48:49]
	v_pk_mul_f32 v[80:81], v[42:43], v[42:43]
	v_pk_mul_f32 v[82:83], v[40:41], v[40:41]
	v_fmac_f32_e32 v36, 0xba800000, v9
	v_fmac_f32_e32 v38, 0xba800000, v9
	v_pk_mov_b32 v[86:87], v[64:65], v[62:63] op_sel:[1,0]
	v_mov_b32_e32 v65, v63
	v_pk_mov_b32 v[62:63], v[82:83], v[80:81] op_sel:[1,0]
	v_mov_b32_e32 v83, v81
	v_fmamk_f32 v37, v9, 0xba800000, v37
	v_fmamk_f32 v39, v9, 0xba800000, v39
	v_mul_f32_e32 v60, v36, v36
	v_mul_f32_e32 v84, v38, v38
	v_pk_add_f32 v[64:65], v[86:87], v[64:65]
	v_pk_add_f32 v[62:63], v[62:63], v[82:83]
	v_fmamk_f32 v45, v9, 0xba800000, v45
	v_fmac_f32_e32 v44, 0xba800000, v9
	v_fmamk_f32 v47, v9, 0xba800000, v47
	v_fmac_f32_e32 v46, 0xba800000, v9
	v_pk_fma_f32 v[80:81], v[36:37], v[36:37], v[60:61] op_sel_hi:[1,1,0]
	v_pk_fma_f32 v[84:85], v[38:39], v[38:39], v[84:85] op_sel_hi:[1,1,0]
	v_pk_add_f32 v[64:65], v[64:65], v[64:65] op_sel_hi:[0,1]
	v_pk_add_f32 v[62:63], v[62:63], v[62:63] op_sel_hi:[0,1]
	v_mul_f32_e32 v80, v46, v46
	v_mul_f32_e32 v84, v47, v47
	v_mul_f32_e32 v64, v44, v44
	v_mul_f32_e32 v62, v45, v45
	v_pk_add_f32 v[80:81], v[80:81], v[84:85]
	v_pk_add_f32 v[62:63], v[64:65], v[62:63]
	s_nop 0
	v_pk_add_f32 v[62:63], v[80:81], v[62:63]
	s_nop 0
	v_add_f32_e32 v9, v62, v63
	v_mov_b32_e32 v29, v9
	s_nop 1
	v_add_f32_dpp v29, v29, v29 quad_perm:[1,0,3,2] row_mask:0xf bank_mask:0xf
	s_nop 1
	v_add_f32_dpp v29, v29, v29 quad_perm:[2,3,0,1] row_mask:0xf bank_mask:0xf
	s_nop 1
	v_add_f32_dpp v29, v29, v29 row_half_mirror row_mask:0xf bank_mask:0xf
	s_nop 1
	v_add_f32_dpp v29, v29, v29 row_mirror row_mask:0xf bank_mask:0xf
	s_nop 0
	v_readlane_b32 s44, v29, 0
	v_readlane_b32 s45, v29, 16
	v_readlane_b32 s46, v29, 32
	v_readlane_b32 s47, v29, 48
	s_nop 1
	v_mov_b32_e32 v29, s44
	v_add_f32_e32 v29, s45, v29
	v_add_f32_e32 v29, s46, v29
	v_add_f32_e32 v29, s47, v29
	v_mov_b32_e32 v9, v29
	v_fmamk_f32 v9, v9, 0x3a800000, v71
	v_mul_f32_e32 v29, 0x4b800000, v9
	v_cmp_gt_f32_e32 vcc, s23, v9
	s_nop 1
	v_cndmask_b32_e32 v9, v9, v29, vcc
	v_rsq_f32_e32 v29, v9
	v_ashrrev_i32_e32 v9, 31, v8
	v_lshlrev_b64 v[8:9], 12, v[8:9]
	v_lshl_add_u64 v[62:63], v[26:27], 0, v[8:9]
	v_mul_f32_e32 v8, 0x45800000, v29
	v_cndmask_b32_e32 v8, v29, v8, vcc
	v_pk_mul_f32 v[48:49], v[48:49], v[8:9] op_sel_hi:[1,0]
	v_pk_mul_f32 v[50:51], v[50:51], v[8:9] op_sel_hi:[1,0]
	s_waitcnt vmcnt(0)
	v_pk_fma_f32 v[48:49], v[52:53], v[48:49], v[56:57]
	v_pk_fma_f32 v[50:51], v[54:55], v[50:51], v[58:59]
	global_store_dwordx4 v[62:63], v[48:51], off
	global_load_dwordx4 v[48:51], v[14:15], off
	s_nop 0
	global_load_dwordx4 v[52:55], v[16:17], off
	v_pk_mul_f32 v[42:43], v[42:43], v[8:9] op_sel_hi:[1,0]
	v_pk_mul_f32 v[40:41], v[40:41], v[8:9] op_sel_hi:[1,0]
	v_pk_mul_f32 v[38:39], v[38:39], v[8:9] op_sel_hi:[1,0]
	v_pk_mul_f32 v[36:37], v[36:37], v[8:9] op_sel_hi:[1,0]
	v_mov_b32_e32 v9, v35
	v_pk_mul_f32 v[56:57], v[44:45], v[8:9] op_sel_hi:[1,0]
	v_pk_mul_f32 v[44:45], v[46:47], v[8:9] op_sel_hi:[1,0]
	v_mov_b32_e32 v8, v34
	s_waitcnt vmcnt(0)
	v_pk_fma_f32 v[40:41], v[48:49], v[40:41], v[52:53]
	v_pk_fma_f32 v[42:43], v[50:51], v[42:43], v[54:55]
	global_store_dwordx4 v[62:63], v[40:43], off offset:1024
	global_load_dwordx4 v[40:43], v[18:19], off
	s_nop 0
	global_load_dwordx4 v[48:51], v[20:21], off
	s_waitcnt vmcnt(0)
	v_pk_fma_f32 v[36:37], v[40:41], v[36:37], v[48:49]
	v_pk_fma_f32 v[38:39], v[42:43], v[38:39], v[50:51]
	global_store_dwordx4 v[62:63], v[36:39], off offset:2048
	global_load_dwordx4 v[48:51], v[22:23], off
	global_load_dwordx4 v[52:55], v[24:25], off
	v_mov_b64_e32 v[42:43], v[72:73]
	v_mov_b64_e32 v[40:41], v[74:75]
	v_mov_b64_e32 v[38:39], v[76:77]
	v_mov_b64_e32 v[36:37], v[78:79]
	s_waitcnt vmcnt(0)
	v_pk_fma_f32 v[44:45], v[48:49], v[44:45], v[52:53]
	v_pk_fma_f32 v[46:47], v[50:51], v[56:57], v[54:55]
	global_store_dwordx4 v[62:63], v[44:47], off offset:3072
	s_andn2_b64 exec, exec, s[8:9]
	s_cbranch_execz .LBB0_1656
